# Hyena item prologue: halo element loads of load_conv no longer wait individually (converted after the wait that covers the row's main loads)
# speedup vs baseline: 1.1312x; 1.0010x over previous
.LBB0_1753:
	s_or_b64 exec, exec, s[6:7]
	v_cmp_gt_i32_e32 vcc, s51, v12
	s_and_saveexec_b64 s[6:7], vcc
	v_lshl_add_u32 v0, v12, 2, v158
	ds_write_b32 v0, v147
	s_or_b64 exec, exec, s[6:7]
	s_or_b32 s70, s22, 0x1000
	s_lshl_b64 s[6:7], s[70:71], 15
	s_add_u32 s6, s86, s6
	v_lshlrev_b32_e32 v16, 4, v12
	s_addc_u32 s7, s87, s7
	v_ashrrev_i32_e32 v17, 31, v16
	v_lshl_add_u64 v[0:1], v[16:17], 1, s[6:7]
	global_load_dwordx4 v[2:5], v[0:1], off offset:16
	global_load_dwordx4 v[6:9], v[0:1], off
	v_and_b32_e32 v19, 0xf0, v16
	v_cmp_ne_u32_e32 vcc, 0, v19
	v_mov_b32_e32 v11, 0
	v_mov_b32_e32 v21, 0
	v_mov_b32_e32 v226, 0
	s_and_saveexec_b64 s[6:7], vcc
	s_cbranch_execz .LBB0_1757
	global_load_ushort v226, v[0:1], off offset:-2
.LBB0_1757:
	s_or_b64 exec, exec, s[6:7]
	s_movk_i32 s6, 0xf0
	v_cmp_ne_u32_e64 s[34:35], s6, v19
	v_mov_b32_e32 v227, 0
	s_and_saveexec_b64 s[8:9], s[34:35]
	s_cbranch_execz .LBB0_1759
	global_load_ushort v227, v[0:1], off offset:32
.LBB0_1759:
	s_or_b64 exec, exec, s[8:9]
	v_readlane_b32 s4, v241, 35
	s_lshl_b64 s[0:1], s[70:71], 2
	v_readlane_b32 s10, v241, 41
	v_readlane_b32 s11, v241, 42
	s_add_u32 s10, s10, s0
	s_addc_u32 s11, s11, s1
	v_readlane_b32 s8, v241, 39
	v_readlane_b32 s12, v241, 43
	s_nop 0
	global_load_dword v15, v147, s[10:11]
	global_load_dword v14, v152, s[10:11]
	global_load_dword v18, v153, s[10:11]
	v_readlane_b32 s9, v241, 40
	v_readlane_b32 s13, v241, 44
	s_add_u32 s8, s12, s0
	s_addc_u32 s9, s13, s1
	s_mov_b32 s23, s71
	s_lshl_b64 s[0:1], s[22:23], 15
	global_load_dword v24, v147, s[8:9]
	s_add_u32 s10, s86, s0
	s_addc_u32 s11, s87, s1
	s_waitcnt vmcnt(4)
	v_lshlrev_b32_e32 v21, 16, v226
	v_lshlrev_b32_e32 v11, 16, v227
	v_pk_mov_b32 v[0:1], v[8:9], v[2:3] op_sel:[1,0]
	v_lshl_add_u64 v[22:23], v[16:17], 1, s[10:11]
	v_lshlrev_b32_e32 v29, 16, v9
	v_and_b32_e32 v28, 0xffff0000, v8
	v_lshlrev_b32_e32 v31, 16, v8
	v_lshlrev_b32_e32 v30, 16, v7
	v_lshlrev_b32_e32 v32, 16, v6
	v_and_b32_e32 v35, 0xffff0000, v7
	v_and_b32_e32 v34, 0xffff0000, v6
	v_lshlrev_b32_e32 v36, 16, v3
	v_lshlrev_b32_e32 v38, 16, v2
	v_and_b32_e32 v41, 0xffff0000, v3
	v_and_b32_e32 v40, 0xffff0000, v2
	v_and_b32_e32 v45, 0xffff0000, v1
	v_and_b32_e32 v44, 0xffff0000, v0
	global_load_dwordx4 v[0:3], v[22:23], off offset:16
	global_load_dwordx4 v[6:9], v[22:23], off
	v_mov_b32_e32 v20, v30
	v_mov_b32_e32 v39, v36
	v_mov_b32_e32 v33, v30
	v_mov_b32_e32 v42, v32
	v_mov_b32_e32 v43, v34
	v_mov_b32_e32 v48, v31
	v_mov_b32_e32 v49, v29
	v_pk_mov_b32 v[46:47], v[34:35], v[28:29] op_sel:[1,0]
	v_lshlrev_b32_e32 v37, 16, v4
	v_mov_b32_e32 v50, v28
	v_mov_b32_e32 v51, v44
	v_pk_mov_b32 v[52:53], v[28:29], v[38:39] op_sel:[1,0]
	v_lshlrev_b32_e32 v27, 16, v5
	v_and_b32_e32 v5, 0xffff0000, v5
	v_and_b32_e32 v4, 0xffff0000, v4
	v_readlane_b32 s5, v241, 36
	v_readlane_b32 s6, v241, 37
	v_readlane_b32 s7, v241, 38
	v_readlane_b32 s14, v241, 45
	v_readlane_b32 s15, v241, 46
	v_readlane_b32 s16, v241, 47
	v_readlane_b32 s17, v241, 48
	v_readlane_b32 s18, v241, 49
	v_readlane_b32 s19, v241, 50
	s_waitcnt vmcnt(5)
	v_mov_b32_e32 v56, v15
	s_waitcnt vmcnt(4)
	v_pk_mul_f32 v[20:21], v[20:21], v[14:15]
	v_pk_mul_f32 v[54:55], v[14:15], v[34:35] op_sel_hi:[0,1]
	v_pk_mul_f32 v[58:59], v[14:15], v[38:39] op_sel_hi:[0,1]
	v_pk_mul_f32 v[60:61], v[14:15], v[40:41] op_sel_hi:[0,1]
	v_pk_mul_f32 v[48:49], v[14:15], v[48:49] op_sel_hi:[0,1]
	v_pk_fma_f32 v[20:21], v[14:15], v[42:43], v[20:21] op_sel:[0,0,1] op_sel_hi:[1,1,0]
	v_pk_fma_f32 v[32:33], v[56:57], v[32:33], v[54:55] op_sel_hi:[0,1,1]
	v_pk_fma_f32 v[42:43], v[56:57], v[44:45], v[58:59] op_sel_hi:[0,1,1]
	v_mov_b32_e32 v45, v31
	v_pk_fma_f32 v[38:39], v[56:57], v[38:39], v[60:61] op_sel_hi:[0,1,1]
	v_pk_fma_f32 v[46:47], v[56:57], v[46:47], v[48:49] op_sel_hi:[0,1,1]
	s_waitcnt vmcnt(3)
	v_pk_fma_f32 v[30:31], v[18:19], v[30:31], v[32:33] op_sel_hi:[0,1,1]
	v_pk_fma_f32 v[32:33], v[18:19], v[40:41], v[42:43] op_sel_hi:[0,1,1]
	v_pk_mul_f32 v[42:43], v[14:15], v[44:45]
	v_pk_fma_f32 v[20:21], v[18:19], v[34:35], v[20:21] op_sel_hi:[0,1,1]
	v_pk_fma_f32 v[34:35], v[18:19], v[36:37], v[38:39] op_sel_hi:[0,1,1]
	v_pk_fma_f32 v[38:39], v[18:19], v[50:51], v[46:47] op_sel_hi:[0,1,1]
	v_pk_fma_f32 v[28:29], v[14:15], v[28:29], v[42:43] op_sel:[0,0,1] op_sel_hi:[1,1,0]
	s_waitcnt vmcnt(2)
	v_pk_add_f32 v[30:31], v[24:25], v[30:31] op_sel_hi:[0,1]
	v_pk_add_f32 v[38:39], v[24:25], v[38:39] op_sel_hi:[0,1]
	v_pk_fma_f32 v[28:29], v[18:19], v[52:53], v[28:29] op_sel_hi:[0,1,1]
	v_pk_add_f32 v[20:21], v[24:25], v[20:21] op_sel_hi:[0,1]
	v_bfe_u32 v10, v31, 16, 1
	v_bfe_u32 v26, v30, 16, 1
	v_bfe_u32 v36, v38, 16, 1
	v_bfe_u32 v42, v39, 16, 1
	v_pk_add_f32 v[28:29], v[24:25], v[28:29] op_sel_hi:[0,1]
	v_bfe_u32 v43, v20, 16, 1
	v_bfe_u32 v44, v21, 16, 1
	v_add3_u32 v26, v30, v26, s50
	v_add3_u32 v10, v31, v10, s50
	v_add3_u32 v30, v39, v42, s50
	v_add3_u32 v31, v38, v36, s50
	v_bfe_u32 v36, v29, 16, 1
	v_bfe_u32 v38, v28, 16, 1
	v_add3_u32 v21, v21, v44, s50
	v_add3_u32 v20, v20, v43, s50
	v_lshrrev_b32_e32 v39, 16, v31
	v_lshrrev_b32_e32 v30, 16, v30
	v_add3_u32 v38, v28, v38, s50
	v_add3_u32 v31, v29, v36, s50
	v_lshrrev_b32_e32 v20, 16, v20
	v_lshrrev_b32_e32 v21, 16, v21
	v_and_or_b32 v31, v31, s52, v30
	v_and_or_b32 v30, v38, s52, v39
	v_mov_b32_e32 v38, v37
	v_mov_b32_e32 v39, v27
	v_and_or_b32 v29, v10, s52, v21
	v_and_or_b32 v28, v26, s52, v20
	v_pk_mov_b32 v[20:21], v[40:41], v[4:5] op_sel:[1,0]
	v_pk_mul_f32 v[38:39], v[14:15], v[38:39] op_sel_hi:[0,1]
	v_pk_fma_f32 v[20:21], v[56:57], v[20:21], v[38:39] op_sel_hi:[0,1,1]
	v_mov_b32_e32 v36, v5
	v_mov_b32_e32 v26, v4
	v_pk_fma_f32 v[20:21], v[18:19], v[4:5], v[20:21] op_sel_hi:[0,1,1]
	v_pk_mul_f32 v[4:5], v[14:15], v[36:37]
	v_mov_b32_e32 v10, v27
	v_pk_fma_f32 v[4:5], v[14:15], v[26:27], v[4:5] op_sel:[0,0,1] op_sel_hi:[1,1,0]
	v_pk_add_f32 v[20:21], v[24:25], v[20:21] op_sel_hi:[0,1]
	v_pk_fma_f32 v[4:5], v[18:19], v[10:11], v[4:5] op_sel_hi:[0,1,1]
	v_pk_add_f32 v[4:5], v[24:25], v[4:5] op_sel_hi:[0,1]
	v_bfe_u32 v14, v5, 16, 1
	v_add3_u32 v5, v5, v14, s50
	v_bfe_u32 v14, v20, 16, 1
	v_pk_add_f32 v[34:35], v[24:25], v[34:35] op_sel_hi:[0,1]
	v_bfe_u32 v15, v4, 16, 1
	v_add3_u32 v14, v20, v14, s50
	v_bfe_u32 v11, v34, 16, 1
	v_add3_u32 v4, v4, v15, s50
	v_lshrrev_b32_e32 v14, 16, v14
	v_pk_add_f32 v[32:33], v[24:25], v[32:33] op_sel_hi:[0,1]
	v_add3_u32 v11, v34, v11, s50
	v_bfe_u32 v15, v21, 16, 1
	v_and_or_b32 v34, v4, s52, v14
	v_ashrrev_i32_e32 v4, 4, v12
	v_bfe_u32 v18, v32, 16, 1
	v_bfe_u32 v24, v33, 16, 1
	v_add3_u32 v15, v21, v15, s50
	v_mul_lo_u32 v4, v4, s53
	v_bfe_u32 v10, v35, 16, 1
	v_add3_u32 v20, v33, v24, s50
	v_add3_u32 v18, v32, v18, s50
	v_lshrrev_b32_e32 v15, 16, v15
	v_lshlrev_b32_e32 v26, 1, v4
	v_lshlrev_b32_e32 v27, 1, v19
	v_add3_u32 v10, v35, v10, s50
	v_lshrrev_b32_e32 v18, 16, v18
	v_lshrrev_b32_e32 v20, 16, v20
	v_and_or_b32 v35, v5, s52, v15
	v_add3_u32 v24, v26, v27, s54
	v_mov_b32_e32 v15, 0
	v_mov_b32_e32 v19, 0
	v_and_or_b32 v33, v10, s52, v20
	v_and_or_b32 v32, v11, s52, v18
	ds_write_b128 v24, v[28:31]
	ds_write_b128 v24, v[32:35] offset:16
	v_mov_b32_e32 v228, 0
	s_and_saveexec_b64 s[10:11], vcc
	s_cbranch_execz .LBB0_1761
	global_load_ushort v228, v[22:23], off offset:-2
.LBB0_1761:
	s_or_b64 exec, exec, s[10:11]
	v_mov_b32_e32 v229, 0
	s_and_saveexec_b64 s[10:11], s[34:35]
	s_cbranch_execz .LBB0_1763
	global_load_ushort v229, v[22:23], off offset:32
.LBB0_1763:
	s_or_b64 exec, exec, s[10:11]
	v_readlane_b32 s4, v241, 35
	v_readlane_b32 s10, v241, 41
	v_readlane_b32 s11, v241, 42
	v_readlane_b32 s18, v241, 49
	v_readlane_b32 s19, v241, 50
	s_lshl_b64 s[2:3], s[22:23], 2
	v_readlane_b32 s12, v241, 43
	v_readlane_b32 s13, v241, 44
	s_mov_b64 s[18:19], s[10:11]
	s_mov_b64 s[20:21], s[12:13]
	s_add_u32 s12, s18, s2
	s_addc_u32 s13, s19, s3
	s_nop 0
	global_load_dword v23, v147, s[12:13]
	global_load_dword v22, v152, s[12:13]
	global_load_dword v32, v153, s[12:13]
	s_add_u32 s12, s20, s2
	s_addc_u32 s13, s21, s3
	global_load_dword v34, v147, s[12:13]
	s_or_b32 s70, s22, 0x800
	s_lshl_b64 s[12:13], s[70:71], 15
	s_add_u32 s12, s86, s12
	s_addc_u32 s13, s87, s13
	v_lshl_add_u64 v[20:21], v[16:17], 1, s[12:13]
	s_waitcnt vmcnt(4)
	v_lshlrev_b32_e32 v19, 16, v228
	v_lshlrev_b32_e32 v15, 16, v229
	v_lshlrev_b32_e32 v29, 16, v9
	v_and_b32_e32 v28, 0xffff0000, v8
	v_lshlrev_b32_e32 v31, 16, v8
	v_lshlrev_b32_e32 v30, 16, v7
	v_lshlrev_b32_e32 v38, 16, v6
	v_and_b32_e32 v41, 0xffff0000, v7
	v_and_b32_e32 v40, 0xffff0000, v6
	v_lshlrev_b32_e32 v42, 16, v1
	v_lshlrev_b32_e32 v44, 16, v0
	v_and_b32_e32 v47, 0xffff0000, v1
	v_and_b32_e32 v46, 0xffff0000, v0
	v_pk_mov_b32 v[0:1], v[8:9], v[0:1] op_sel:[1,0]
	global_load_dwordx4 v[4:7], v[20:21], off offset:16
	global_load_dwordx4 v[8:11], v[20:21], off
	v_mov_b32_e32 v18, v30
	v_mov_b32_e32 v45, v42
	v_mov_b32_e32 v48, v38
	v_mov_b32_e32 v49, v40
	v_and_b32_e32 v1, 0xffff0000, v1
	v_and_b32_e32 v0, 0xffff0000, v0
	v_mov_b32_e32 v52, v31
	v_mov_b32_e32 v53, v29
	v_mov_b32_e32 v39, v30
	v_pk_mov_b32 v[50:51], v[40:41], v[28:29] op_sel:[1,0]
	v_lshlrev_b32_e32 v43, 16, v2
	v_mov_b32_e32 v54, v28
	v_mov_b32_e32 v55, v0
	v_pk_mov_b32 v[56:57], v[28:29], v[44:45] op_sel:[1,0]
	v_lshlrev_b32_e32 v37, 16, v3
	v_readlane_b32 s5, v241, 36
	v_readlane_b32 s6, v241, 37
	v_readlane_b32 s7, v241, 38
	v_readlane_b32 s8, v241, 39
	v_readlane_b32 s9, v241, 40
	v_readlane_b32 s14, v241, 45
	v_readlane_b32 s15, v241, 46
	v_readlane_b32 s16, v241, 47
	v_readlane_b32 s17, v241, 48
	s_waitcnt vmcnt(5)
	v_mov_b32_e32 v60, v23
	s_waitcnt vmcnt(4)
	v_pk_mul_f32 v[18:19], v[18:19], v[22:23]
	v_pk_mul_f32 v[62:63], v[22:23], v[44:45] op_sel_hi:[0,1]
	v_pk_mul_f32 v[58:59], v[22:23], v[40:41] op_sel_hi:[0,1]
	v_pk_mul_f32 v[64:65], v[22:23], v[46:47] op_sel_hi:[0,1]
	v_pk_mul_f32 v[52:53], v[22:23], v[52:53] op_sel_hi:[0,1]
	v_pk_fma_f32 v[18:19], v[22:23], v[48:49], v[18:19] op_sel:[0,0,1] op_sel_hi:[1,1,0]
	v_pk_fma_f32 v[48:49], v[60:61], v[0:1], v[62:63] op_sel_hi:[0,1,1]
	v_mov_b32_e32 v1, v31
	v_pk_fma_f32 v[38:39], v[60:61], v[38:39], v[58:59] op_sel_hi:[0,1,1]
	v_pk_fma_f32 v[44:45], v[60:61], v[44:45], v[64:65] op_sel_hi:[0,1,1]
	v_pk_fma_f32 v[50:51], v[60:61], v[50:51], v[52:53] op_sel_hi:[0,1,1]
	s_waitcnt vmcnt(3)
	v_pk_fma_f32 v[18:19], v[32:33], v[40:41], v[18:19] op_sel_hi:[0,1,1]
	v_pk_mul_f32 v[0:1], v[22:23], v[0:1]
	v_pk_fma_f32 v[30:31], v[32:33], v[30:31], v[38:39] op_sel_hi:[0,1,1]
	v_pk_fma_f32 v[38:39], v[32:33], v[46:47], v[48:49] op_sel_hi:[0,1,1]
	v_pk_fma_f32 v[40:41], v[32:33], v[42:43], v[44:45] op_sel_hi:[0,1,1]
	v_pk_fma_f32 v[44:45], v[32:33], v[54:55], v[50:51] op_sel_hi:[0,1,1]
	s_waitcnt vmcnt(2)
	v_pk_add_f32 v[18:19], v[34:35], v[18:19] op_sel_hi:[0,1]
	v_pk_fma_f32 v[0:1], v[22:23], v[28:29], v[0:1] op_sel:[0,0,1] op_sel_hi:[1,1,0]
	v_pk_add_f32 v[30:31], v[34:35], v[30:31] op_sel_hi:[0,1]
	v_pk_add_f32 v[38:39], v[34:35], v[38:39] op_sel_hi:[0,1]
	v_pk_add_f32 v[40:41], v[34:35], v[40:41] op_sel_hi:[0,1]
	v_pk_add_f32 v[44:45], v[34:35], v[44:45] op_sel_hi:[0,1]
	v_pk_fma_f32 v[0:1], v[32:33], v[56:57], v[0:1] op_sel_hi:[0,1,1]
	v_bfe_u32 v35, v18, 16, 1
	v_bfe_u32 v14, v31, 16, 1
	v_bfe_u32 v28, v30, 16, 1
	v_bfe_u32 v29, v44, 16, 1
	v_bfe_u32 v33, v45, 16, 1
	v_bfe_u32 v36, v19, 16, 1
	v_pk_add_f32 v[0:1], v[34:35], v[0:1] op_sel_hi:[0,1]
	v_add3_u32 v28, v30, v28, s50
	v_add3_u32 v14, v31, v14, s50
	v_add3_u32 v19, v19, v36, s50
	v_add3_u32 v18, v18, v35, s50
	v_add3_u32 v30, v45, v33, s50
	v_add3_u32 v29, v44, v29, s50
	v_bfe_u32 v31, v1, 16, 1
	v_bfe_u32 v33, v0, 16, 1
	v_lshrrev_b32_e32 v35, 16, v29
	v_lshrrev_b32_e32 v30, 16, v30
	v_lshrrev_b32_e32 v18, 16, v18
	v_lshrrev_b32_e32 v19, 16, v19
	v_add3_u32 v0, v0, v33, s50
	v_add3_u32 v1, v1, v31, s50
	v_and_or_b32 v29, v14, s52, v19
	v_and_or_b32 v28, v28, s52, v18
	v_and_or_b32 v31, v1, s52, v30
	v_and_or_b32 v30, v0, s52, v35
	v_and_b32_e32 v1, 0xffff0000, v3
	v_and_b32_e32 v0, 0xffff0000, v2
	v_mov_b32_e32 v18, v43
	v_mov_b32_e32 v19, v37
	v_pk_mov_b32 v[2:3], v[46:47], v[0:1] op_sel:[1,0]
	v_pk_mul_f32 v[18:19], v[22:23], v[18:19] op_sel_hi:[0,1]
	v_pk_fma_f32 v[2:3], v[60:61], v[2:3], v[18:19] op_sel_hi:[0,1,1]
	v_mov_b32_e32 v42, v1
	v_mov_b32_e32 v36, v0
	v_pk_fma_f32 v[2:3], v[32:33], v[0:1], v[2:3] op_sel_hi:[0,1,1]
	v_pk_mul_f32 v[0:1], v[22:23], v[42:43]
	v_mov_b32_e32 v14, v37
	v_pk_fma_f32 v[0:1], v[22:23], v[36:37], v[0:1] op_sel:[0,0,1] op_sel_hi:[1,1,0]
	v_pk_add_f32 v[2:3], v[34:35], v[2:3] op_sel_hi:[0,1]
	v_pk_fma_f32 v[0:1], v[32:33], v[14:15], v[0:1] op_sel_hi:[0,1,1]
	v_pk_add_f32 v[0:1], v[34:35], v[0:1] op_sel_hi:[0,1]
	v_bfe_u32 v14, v41, 16, 1
	v_bfe_u32 v15, v40, 16, 1
	v_bfe_u32 v18, v1, 16, 1
	v_bfe_u32 v19, v0, 16, 1
	v_add3_u32 v19, v0, v19, s50
	v_add3_u32 v18, v1, v18, s50
	v_add3_u32 v0, v40, v15, s50
	v_add3_u32 v1, v41, v14, s50
	v_bfe_u32 v14, v2, 16, 1
	v_bfe_u32 v15, v3, 16, 1
	v_bfe_u32 v23, v39, 16, 1
	v_bfe_u32 v22, v38, 16, 1
	v_add3_u32 v3, v3, v15, s50
	v_add3_u32 v2, v2, v14, s50
	v_add3_u32 v14, v39, v23, s50
	v_add3_u32 v15, v38, v22, s50
	v_lshrrev_b32_e32 v3, 16, v3
	v_lshrrev_b32_e32 v14, 16, v14
	v_lshrrev_b32_e32 v2, 16, v2
	v_lshrrev_b32_e32 v15, 16, v15
	v_and_or_b32 v1, v1, s52, v14
	v_and_or_b32 v3, v18, s52, v3
	v_add3_u32 v14, v26, v27, s55
	v_and_or_b32 v0, v0, s52, v15
	v_and_or_b32 v2, v19, s52, v2
	ds_write_b128 v14, v[28:31]
	ds_write_b128 v14, v[0:3] offset:16
	v_mov_b32_e32 v1, 0
	v_mov_b32_e32 v3, 0
	v_mov_b32_e32 v230, 0
	s_and_saveexec_b64 s[12:13], vcc
	s_cbranch_execz .LBB0_1765
	global_load_ushort v230, v[20:21], off offset:-2
.LBB0_1765:
	s_or_b64 exec, exec, s[12:13]
	v_mov_b32_e32 v231, 0
	s_and_saveexec_b64 s[12:13], s[34:35]
	s_cbranch_execz .LBB0_1767
	global_load_ushort v231, v[20:21], off offset:32
.LBB0_1767:
	s_or_b64 exec, exec, s[12:13]
	v_readlane_b32 s8, v241, 35
	s_lshl_b64 s[6:7], s[70:71], 2
	v_readlane_b32 s12, v241, 39
	v_readlane_b32 s14, v241, 41
	v_readlane_b32 s13, v241, 40
	v_readlane_b32 s15, v241, 42
	s_add_u32 s12, s14, s6
	v_readlane_b32 s16, v241, 43
	s_addc_u32 s13, s15, s7
	v_readlane_b32 s17, v241, 44
	global_load_dword v15, v147, s[12:13]
	global_load_dword v14, v152, s[12:13]
	global_load_dword v18, v153, s[12:13]
	s_add_u32 s12, s16, s6
	s_addc_u32 s13, s17, s7
	global_load_dword v20, v147, s[12:13]
	s_waitcnt vmcnt(4)
	v_lshlrev_b32_e32 v3, 16, v230
	v_lshlrev_b32_e32 v1, 16, v231
	v_and_b32_e32 v28, 0xffff0000, v10
	v_lshlrev_b32_e32 v31, 16, v10
	v_lshlrev_b32_e32 v30, 16, v9
	v_lshlrev_b32_e32 v10, 16, v8
	v_lshlrev_b32_e32 v32, 16, v5
	v_lshlrev_b32_e32 v29, 16, v11
	v_and_b32_e32 v9, 0xffff0000, v9
	v_and_b32_e32 v8, 0xffff0000, v8
	v_lshlrev_b32_e32 v34, 16, v4
	v_and_b32_e32 v37, 0xffff0000, v5
	v_and_b32_e32 v36, 0xffff0000, v4
	v_pk_mov_b32 v[4:5], v[10:11], v[4:5] op_sel:[1,0]
	v_mov_b32_e32 v2, v30
	v_mov_b32_e32 v35, v32
	v_mov_b32_e32 v11, v30
	v_mov_b32_e32 v38, v10
	v_mov_b32_e32 v39, v8
	v_and_b32_e32 v5, 0xffff0000, v5
	v_and_b32_e32 v4, 0xffff0000, v4
	v_mov_b32_e32 v42, v31
	v_mov_b32_e32 v43, v29
	v_lshrrev_b32_e32 v19, 5, v25
	v_pk_mov_b32 v[40:41], v[8:9], v[28:29] op_sel:[1,0]
	v_lshlrev_b32_e32 v33, 16, v6
	v_mov_b32_e32 v44, v28
	v_mov_b32_e32 v45, v4
	v_pk_mov_b32 v[46:47], v[28:29], v[34:35] op_sel:[1,0]
	v_lshlrev_b32_e32 v23, 16, v7
	v_and_b32_e32 v7, 0xffff0000, v7
	v_and_b32_e32 v6, 0xffff0000, v6
	v_mov_b32_e32 v22, v6
	v_mov_b32_e32 v0, v23
	s_movk_i32 s4, 0x440
	v_and_b32_e32 v25, 31, v12
	v_readlane_b32 s9, v241, 36
	v_readlane_b32 s10, v241, 37
	v_readlane_b32 s11, v241, 38
	v_readlane_b32 s18, v241, 45
	v_readlane_b32 s19, v241, 46
	v_readlane_b32 s20, v241, 47
	v_readlane_b32 s21, v241, 48
	v_readlane_b32 s22, v241, 49
	v_readlane_b32 s23, v241, 50
	v_readlane_b32 s8, v241, 3
	v_readlane_b32 s10, v241, 5
	v_readlane_b32 s14, v241, 9
	v_readlane_b32 s11, v241, 6
	v_readlane_b32 s15, v241, 10
	s_add_u32 s10, s14, s2
	s_addc_u32 s11, s15, s3
	s_add_u32 s6, s14, s6
	s_addc_u32 s7, s15, s7
	v_readlane_b32 s2, v240, 12
	v_readlane_b32 s3, v240, 13
	v_add_u32_e32 v162, 16, v24
	v_readlane_b32 s9, v241, 4
	v_readlane_b32 s12, v241, 7
	v_readlane_b32 s13, v241, 8
	v_readlane_b32 s16, v241, 11
	v_readlane_b32 s17, v241, 12
	v_readlane_b32 s18, v241, 13
	v_readlane_b32 s19, v241, 14
	v_readlane_b32 s20, v241, 15
	v_readlane_b32 s21, v241, 16
	v_readlane_b32 s22, v241, 17
	v_readlane_b32 s23, v241, 18
	s_waitcnt vmcnt(3)
	v_mov_b32_e32 v50, v15
	s_waitcnt vmcnt(2)
	v_pk_mul_f32 v[2:3], v[2:3], v[14:15]
	v_pk_mul_f32 v[48:49], v[14:15], v[8:9] op_sel_hi:[0,1]
	v_pk_mul_f32 v[52:53], v[14:15], v[34:35] op_sel_hi:[0,1]
	v_pk_mul_f32 v[54:55], v[14:15], v[36:37] op_sel_hi:[0,1]
	v_pk_mul_f32 v[42:43], v[14:15], v[42:43] op_sel_hi:[0,1]
	v_pk_fma_f32 v[2:3], v[14:15], v[38:39], v[2:3] op_sel:[0,0,1] op_sel_hi:[1,1,0]
	v_pk_fma_f32 v[10:11], v[50:51], v[10:11], v[48:49] op_sel_hi:[0,1,1]
	v_pk_fma_f32 v[38:39], v[50:51], v[4:5], v[52:53] op_sel_hi:[0,1,1]
	v_mov_b32_e32 v5, v31
	v_pk_fma_f32 v[34:35], v[50:51], v[34:35], v[54:55] op_sel_hi:[0,1,1]
	v_pk_fma_f32 v[40:41], v[50:51], v[40:41], v[42:43] op_sel_hi:[0,1,1]
	s_waitcnt vmcnt(1)
	v_pk_fma_f32 v[2:3], v[18:19], v[8:9], v[2:3] op_sel_hi:[0,1,1]
	v_pk_fma_f32 v[8:9], v[18:19], v[30:31], v[10:11] op_sel_hi:[0,1,1]
	v_pk_mul_f32 v[4:5], v[14:15], v[4:5]
	v_pk_fma_f32 v[10:11], v[18:19], v[36:37], v[38:39] op_sel_hi:[0,1,1]
	v_pk_fma_f32 v[30:31], v[18:19], v[32:33], v[34:35] op_sel_hi:[0,1,1]
	v_pk_fma_f32 v[34:35], v[18:19], v[44:45], v[40:41] op_sel_hi:[0,1,1]
	s_waitcnt vmcnt(0)
	v_pk_add_f32 v[8:9], v[20:21], v[8:9] op_sel_hi:[0,1]
	v_pk_fma_f32 v[4:5], v[14:15], v[28:29], v[4:5] op_sel:[0,0,1] op_sel_hi:[1,1,0]
	v_pk_add_f32 v[2:3], v[20:21], v[2:3] op_sel_hi:[0,1]
	v_pk_add_f32 v[10:11], v[20:21], v[10:11] op_sel_hi:[0,1]
	v_pk_add_f32 v[30:31], v[20:21], v[30:31] op_sel_hi:[0,1]
	v_pk_add_f32 v[34:35], v[20:21], v[34:35] op_sel_hi:[0,1]
	v_pk_fma_f32 v[4:5], v[18:19], v[46:47], v[4:5] op_sel_hi:[0,1,1]
	v_bfe_u32 v21, v9, 16, 1
	v_bfe_u32 v28, v8, 16, 1
	v_bfe_u32 v29, v34, 16, 1
	v_bfe_u32 v32, v35, 16, 1
	v_pk_add_f32 v[4:5], v[20:21], v[4:5] op_sel_hi:[0,1]
	v_bfe_u32 v38, v2, 16, 1
	v_bfe_u32 v39, v3, 16, 1
	v_add3_u32 v8, v8, v28, s50
	v_add3_u32 v9, v9, v21, s50
	v_add3_u32 v21, v35, v32, s50
	v_add3_u32 v28, v34, v29, s50
	v_bfe_u32 v32, v4, 16, 1
	v_add3_u32 v3, v3, v39, s50
	v_add3_u32 v2, v2, v38, s50
	v_bfe_u32 v29, v5, 16, 1
	v_lshrrev_b32_e32 v28, 16, v28
	v_add3_u32 v4, v4, v32, s50
	v_lshrrev_b32_e32 v2, 16, v2
	v_lshrrev_b32_e32 v3, 16, v3
	v_add3_u32 v5, v5, v29, s50
	v_and_or_b32 v4, v4, s52, v28
	v_mov_b32_e32 v28, v33
	v_mov_b32_e32 v29, v23
	v_and_or_b32 v3, v9, s52, v3
	v_and_or_b32 v2, v8, s52, v2
	v_pk_mov_b32 v[8:9], v[36:37], v[6:7] op_sel:[1,0]
	v_pk_mul_f32 v[28:29], v[14:15], v[28:29] op_sel_hi:[0,1]
	v_pk_fma_f32 v[8:9], v[50:51], v[8:9], v[28:29] op_sel_hi:[0,1,1]
	v_mov_b32_e32 v32, v7
	v_pk_fma_f32 v[8:9], v[18:19], v[6:7], v[8:9] op_sel_hi:[0,1,1]
	v_pk_mul_f32 v[6:7], v[14:15], v[32:33]
	v_lshrrev_b32_e32 v21, 16, v21
	v_pk_fma_f32 v[6:7], v[14:15], v[22:23], v[6:7] op_sel:[0,0,1] op_sel_hi:[1,1,0]
	v_pk_add_f32 v[8:9], v[20:21], v[8:9] op_sel_hi:[0,1]
	v_pk_fma_f32 v[0:1], v[18:19], v[0:1], v[6:7] op_sel_hi:[0,1,1]
	v_pk_add_f32 v[0:1], v[20:21], v[0:1] op_sel_hi:[0,1]
	v_bfe_u32 v7, v30, 16, 1
	v_bfe_u32 v14, v1, 16, 1
	v_bfe_u32 v15, v0, 16, 1
	v_add3_u32 v1, v1, v14, s50
	v_add3_u32 v14, v30, v7, s50
	v_bfe_u32 v7, v8, 16, 1
	v_add3_u32 v0, v0, v15, s50
	v_bfe_u32 v15, v9, 16, 1
	v_bfe_u32 v18, v10, 16, 1
	v_bfe_u32 v20, v11, 16, 1
	v_add3_u32 v7, v8, v7, s50
	v_bfe_u32 v6, v31, 16, 1
	v_add3_u32 v9, v9, v15, s50
	v_add3_u32 v8, v11, v20, s50
	v_add3_u32 v10, v10, v18, s50
	v_lshrrev_b32_e32 v11, 16, v7
	v_and_or_b32 v5, v5, s52, v21
	v_add3_u32 v6, v31, v6, s50
	v_lshrrev_b32_e32 v9, 16, v9
	v_lshrrev_b32_e32 v10, 16, v10
	v_lshrrev_b32_e32 v7, 16, v8
	v_and_or_b32 v8, v0, s52, v11
	v_add3_u32 v0, v26, v27, s56
	v_lshlrev_b32_e32 v39, 5, v13
	v_and_or_b32 v7, v6, s52, v7
	v_and_or_b32 v6, v14, s52, v10
	v_and_or_b32 v9, v1, s52, v9
	ds_write_b128 v0, v[2:5]
	ds_write_b128 v0, v[6:9] offset:16
	v_bitop3_b32 v1, v12, s49, 31 bitop3:0x6c
	v_bitop3_b32 v2, v12, v39, 1 bitop3:0xce
	v_lshlrev_b32_e32 v38, 3, v19
	v_sub_u32_e32 v1, v1, v2
	v_add_lshl_u32 v1, v1, v38, 1
	v_bitop3_b32 v0, v12, 1, v12 bitop3:0xc
	v_and_b32_e32 v1, -4, v1
	v_mad_u32_u24 v18, v0, s4, v1
	s_waitcnt lgkmcnt(0)
	s_barrier
	v_mul_u32_u24_e32 v4, 0x108, v25
	ds_read2_b32 v[0:1], v18 offset1:1
	ds_read2_b32 v[2:3], v18 offset0:2 offset1:3
	v_lshlrev_b32_e32 v5, 4, v19
	v_lshl_add_u32 v43, v4, 1, v5
	v_add_u32_e32 v19, 0x10400, v43
	ds_read_b128 v[4:7], v19
	ds_read_b128 v[20:23], v19 offset:32
	ds_read2_b32 v[26:27], v18 offset0:8 offset1:9
	ds_read2_b32 v[28:29], v18 offset0:10 offset1:11
	s_waitcnt lgkmcnt(3)
	v_mfma_f32_32x32x16_bf16 v[0:15], v[0:3], v[4:7], 0
	v_add_u32_e32 v51, 0x14600, v43
	s_waitcnt lgkmcnt(0)
	v_mfma_f32_32x32x16_bf16 v[0:15], v[26:29], v[20:23], v[0:15]
	ds_read2_b32 v[20:21], v18 offset0:16 offset1:17
	ds_read2_b32 v[22:23], v18 offset0:18 offset1:19
	ds_read_b128 v[26:29], v19 offset:64
	ds_read_b128 v[30:33], v19 offset:96
	ds_read2_b32 v[34:35], v18 offset0:24 offset1:25
	ds_read2_b32 v[36:37], v18 offset0:26 offset1:27
	s_waitcnt lgkmcnt(3)
	v_mfma_f32_32x32x16_bf16 v[0:15], v[20:23], v[26:29], v[0:15]
	s_waitcnt lgkmcnt(0)
	v_mfma_f32_32x32x16_bf16 v[0:15], v[34:37], v[30:33], v[0:15]
	ds_read2_b32 v[20:21], v18 offset0:32 offset1:33
	ds_read2_b32 v[22:23], v18 offset0:34 offset1:35
	ds_read_b128 v[26:29], v19 offset:128
	ds_read_b128 v[30:33], v19 offset:160
	ds_read2_b32 v[34:35], v18 offset0:40 offset1:41
	ds_read2_b32 v[36:37], v18 offset0:42 offset1:43
	s_waitcnt lgkmcnt(3)
	v_mfma_f32_32x32x16_bf16 v[0:15], v[20:23], v[26:29], v[0:15]
	s_waitcnt lgkmcnt(0)
	v_mfma_f32_32x32x16_bf16 v[0:15], v[34:37], v[30:33], v[0:15]
	ds_read2_b32 v[20:21], v18 offset0:48 offset1:49
	ds_read2_b32 v[22:23], v18 offset0:50 offset1:51
	ds_read_b128 v[26:29], v19 offset:192
	ds_read_b128 v[30:33], v19 offset:224
	ds_read2_b32 v[34:35], v18 offset0:56 offset1:57
	ds_read2_b32 v[36:37], v18 offset0:58 offset1:59
	s_waitcnt lgkmcnt(3)
	v_mfma_f32_32x32x16_bf16 v[0:15], v[20:23], v[26:29], v[0:15]
	s_waitcnt lgkmcnt(0)
	v_mfma_f32_32x32x16_bf16 v[0:15], v[34:37], v[30:33], v[0:15]
	ds_read2_b32 v[20:21], v18 offset0:64 offset1:65
	ds_read2_b32 v[22:23], v18 offset0:66 offset1:67
	ds_read_b128 v[26:29], v19 offset:256
	ds_read_b128 v[30:33], v19 offset:288
	ds_read2_b32 v[34:35], v18 offset0:72 offset1:73
	ds_read2_b32 v[36:37], v18 offset0:74 offset1:75
	s_waitcnt lgkmcnt(3)
	v_mfma_f32_32x32x16_bf16 v[0:15], v[20:23], v[26:29], v[0:15]
	s_waitcnt lgkmcnt(0)
	v_mfma_f32_32x32x16_bf16 v[0:15], v[34:37], v[30:33], v[0:15]
	ds_read2_b32 v[20:21], v18 offset0:80 offset1:81
	ds_read2_b32 v[22:23], v18 offset0:82 offset1:83
	ds_read_b128 v[26:29], v19 offset:320
	ds_read_b128 v[30:33], v19 offset:352
	ds_read2_b32 v[34:35], v18 offset0:88 offset1:89
	ds_read2_b32 v[36:37], v18 offset0:90 offset1:91
	s_waitcnt lgkmcnt(3)
	v_mfma_f32_32x32x16_bf16 v[0:15], v[20:23], v[26:29], v[0:15]
	s_waitcnt lgkmcnt(0)
	v_mfma_f32_32x32x16_bf16 v[0:15], v[34:37], v[30:33], v[0:15]
	ds_read2_b32 v[20:21], v18 offset0:96 offset1:97
	ds_read2_b32 v[22:23], v18 offset0:98 offset1:99
	ds_read_b128 v[26:29], v19 offset:384
	ds_read_b128 v[30:33], v19 offset:416
	ds_read2_b32 v[34:35], v18 offset0:104 offset1:105
	ds_read2_b32 v[36:37], v18 offset0:106 offset1:107
	global_load_dword v42, v147, s[10:11]
	s_waitcnt lgkmcnt(3)
	v_mfma_f32_32x32x16_bf16 v[0:15], v[20:23], v[26:29], v[0:15]
	s_waitcnt lgkmcnt(0)
	v_mfma_f32_32x32x16_bf16 v[0:15], v[34:37], v[30:33], v[0:15]
	ds_read2_b32 v[26:27], v18 offset0:112 offset1:113
	ds_read2_b32 v[28:29], v18 offset0:114 offset1:115
	ds_read_b128 v[30:33], v19 offset:448
	ds_read_b128 v[34:37], v19 offset:480
	v_mad_u32_u24 v19, v25, s53, v39
	v_lshl_or_b32 v19, v19, 1, v38
	v_add_u32_e32 v20, 0x10400, v19
	ds_read_b64 v[22:23], v20
	ds_read2_b32 v[38:39], v18 offset0:120 offset1:121
	ds_read2_b32 v[40:41], v18 offset0:122 offset1:123
	v_add_u32_e32 v21, 0x18800, v19
	v_add_u32_e32 v25, 0x14600, v19
	s_waitcnt lgkmcnt(4)
	v_mfma_f32_32x32x16_bf16 v[0:15], v[26:29], v[30:33], v[0:15]
	ds_read_b64 v[26:27], v21
	s_waitcnt lgkmcnt(3)
	v_lshlrev_b32_e32 v29, 16, v23
	v_lshlrev_b32_e32 v28, 16, v22
	v_and_b32_e32 v23, 0xffff0000, v23
	v_and_b32_e32 v22, 0xffff0000, v22
	s_waitcnt lgkmcnt(0)
	v_lshlrev_b32_e32 v31, 16, v27
	v_lshlrev_b32_e32 v30, 16, v26
	v_mfma_f32_32x32x16_bf16 v[0:15], v[38:41], v[34:37], v[0:15]
	v_and_b32_e32 v27, 0xffff0000, v27
	v_and_b32_e32 v26, 0xffff0000, v26
	v_add_u32_e32 v48, 0x14610, v19
	v_add_u32_e32 v49, 0x14620, v19
	v_add_u32_e32 v50, 0x14630, v19
	s_nop 6
	v_mov_b32_e32 v32, v0
	v_mov_b32_e32 v33, v2
	v_mov_b32_e32 v2, v1
	s_waitcnt vmcnt(0)
	v_pk_fma_f32 v[0:1], v[42:43], v[28:29], v[32:33] op_sel_hi:[0,1,1]
	v_pk_mul_f32 v[0:1], v[0:1], v[30:31]
	v_pk_fma_f32 v[2:3], v[42:43], v[22:23], v[2:3] op_sel_hi:[0,1,1]
	v_pk_mul_f32 v[2:3], v[2:3], v[26:27]
	v_and_b32_sdwa v21, v1, v159 dst_sel:DWORD dst_unused:UNUSED_PAD src0_sel:WORD_1 src1_sel:DWORD
	v_and_b32_sdwa v22, v0, v159 dst_sel:DWORD dst_unused:UNUSED_PAD src0_sel:WORD_1 src1_sel:DWORD
	v_add3_u32 v0, v0, v22, s50
	v_add3_u32 v1, v1, v21, s50
	v_and_b32_sdwa v21, v3, v159 dst_sel:DWORD dst_unused:UNUSED_PAD src0_sel:WORD_1 src1_sel:DWORD
	v_and_b32_sdwa v22, v2, v159 dst_sel:DWORD dst_unused:UNUSED_PAD src0_sel:WORD_1 src1_sel:DWORD
	v_add3_u32 v3, v3, v21, s50
	v_add3_u32 v2, v2, v22, s50
	v_and_b32_e32 v3, 0xffff0000, v3
	v_and_b32_e32 v2, 0xffff0000, v2
	v_or_b32_sdwa v1, v3, v1 dst_sel:DWORD dst_unused:UNUSED_PAD src0_sel:DWORD src1_sel:WORD_1
	v_or_b32_sdwa v0, v2, v0 dst_sel:DWORD dst_unused:UNUSED_PAD src0_sel:DWORD src1_sel:WORD_1
	ds_write_b64 v25, v[0:1]
	v_add_u32_e32 v21, 0x10410, v19
	ds_read_b64 v[0:1], v21
	v_add_u32_e32 v2, 0x18810, v19
	ds_read_b64 v[2:3], v2
	v_mov_b32_e32 v29, v6
	v_mov_b32_e32 v6, v5
	s_waitcnt lgkmcnt(1)
	v_lshlrev_b32_e32 v23, 16, v1
	v_lshlrev_b32_e32 v22, 16, v0
	v_and_b32_e32 v1, 0xffff0000, v1
	v_and_b32_e32 v0, 0xffff0000, v0
	s_waitcnt lgkmcnt(0)
	v_lshlrev_b32_e32 v27, 16, v3
	v_lshlrev_b32_e32 v26, 16, v2
	v_and_b32_e32 v3, 0xffff0000, v3
	v_and_b32_e32 v2, 0xffff0000, v2
	v_mov_b32_e32 v28, v4
	v_pk_fma_f32 v[0:1], v[42:43], v[0:1], v[6:7] op_sel_hi:[0,1,1]
	v_pk_fma_f32 v[22:23], v[42:43], v[22:23], v[28:29] op_sel_hi:[0,1,1]
	v_pk_mul_f32 v[0:1], v[0:1], v[2:3]
	v_pk_mul_f32 v[22:23], v[22:23], v[26:27]
	v_and_b32_sdwa v4, v1, v159 dst_sel:DWORD dst_unused:UNUSED_PAD src0_sel:WORD_1 src1_sel:DWORD
	v_and_b32_sdwa v5, v0, v159 dst_sel:DWORD dst_unused:UNUSED_PAD src0_sel:WORD_1 src1_sel:DWORD
	v_and_b32_sdwa v2, v23, v159 dst_sel:DWORD dst_unused:UNUSED_PAD src0_sel:WORD_1 src1_sel:DWORD
	v_and_b32_sdwa v3, v22, v159 dst_sel:DWORD dst_unused:UNUSED_PAD src0_sel:WORD_1 src1_sel:DWORD
	v_add3_u32 v1, v1, v4, s50
	v_add3_u32 v0, v0, v5, s50
	v_add3_u32 v3, v22, v3, s50
	v_add3_u32 v2, v23, v2, s50
	v_and_b32_e32 v1, 0xffff0000, v1
	v_and_b32_e32 v0, 0xffff0000, v0
	v_or_b32_sdwa v1, v1, v2 dst_sel:DWORD dst_unused:UNUSED_PAD src0_sel:DWORD src1_sel:WORD_1
	v_or_b32_sdwa v0, v0, v3 dst_sel:DWORD dst_unused:UNUSED_PAD src0_sel:DWORD src1_sel:WORD_1
	ds_write_b64 v48, v[0:1]
	v_add_u32_e32 v22, 0x10420, v19
	ds_read_b64 v[0:1], v22
	v_add_u32_e32 v2, 0x18820, v19
	ds_read_b64 v[2:3], v2
	v_mov_b32_e32 v26, v8
	v_mov_b32_e32 v27, v10
	s_waitcnt lgkmcnt(1)
	v_lshlrev_b32_e32 v5, 16, v1
	v_lshlrev_b32_e32 v4, 16, v0
	v_and_b32_e32 v1, 0xffff0000, v1
	v_and_b32_e32 v0, 0xffff0000, v0
	s_waitcnt lgkmcnt(0)
	v_lshlrev_b32_e32 v7, 16, v3
	v_lshlrev_b32_e32 v6, 16, v2
	v_pk_fma_f32 v[4:5], v[42:43], v[4:5], v[26:27] op_sel_hi:[0,1,1]
	v_mov_b32_e32 v10, v9
	v_and_b32_e32 v3, 0xffff0000, v3
	v_and_b32_e32 v2, 0xffff0000, v2
	v_pk_mul_f32 v[4:5], v[4:5], v[6:7]
	v_pk_fma_f32 v[0:1], v[42:43], v[0:1], v[10:11] op_sel_hi:[0,1,1]
	v_pk_mul_f32 v[0:1], v[0:1], v[2:3]
	v_and_b32_sdwa v2, v5, v159 dst_sel:DWORD dst_unused:UNUSED_PAD src0_sel:WORD_1 src1_sel:DWORD
	v_and_b32_sdwa v3, v4, v159 dst_sel:DWORD dst_unused:UNUSED_PAD src0_sel:WORD_1 src1_sel:DWORD
	v_add3_u32 v3, v4, v3, s50
	v_add3_u32 v2, v5, v2, s50
	v_and_b32_sdwa v4, v1, v159 dst_sel:DWORD dst_unused:UNUSED_PAD src0_sel:WORD_1 src1_sel:DWORD
	v_and_b32_sdwa v5, v0, v159 dst_sel:DWORD dst_unused:UNUSED_PAD src0_sel:WORD_1 src1_sel:DWORD
	v_add3_u32 v1, v1, v4, s50
	v_add3_u32 v0, v0, v5, s50
	v_and_b32_e32 v1, 0xffff0000, v1
	v_and_b32_e32 v0, 0xffff0000, v0
	v_or_b32_sdwa v1, v1, v2 dst_sel:DWORD dst_unused:UNUSED_PAD src0_sel:DWORD src1_sel:WORD_1
	v_or_b32_sdwa v0, v0, v3 dst_sel:DWORD dst_unused:UNUSED_PAD src0_sel:DWORD src1_sel:WORD_1
	ds_write_b64 v49, v[0:1]
	v_add_u32_e32 v23, 0x10430, v19
	ds_read_b64 v[0:1], v23
	v_add_u32_e32 v2, 0x18830, v19
	ds_read_b64 v[2:3], v2
	v_mov_b32_e32 v8, v12
	v_mov_b32_e32 v9, v14
	s_waitcnt lgkmcnt(1)
	v_lshlrev_b32_e32 v5, 16, v1
	v_lshlrev_b32_e32 v4, 16, v0
	v_and_b32_e32 v1, 0xffff0000, v1
	v_and_b32_e32 v0, 0xffff0000, v0
	s_waitcnt lgkmcnt(0)
	v_lshlrev_b32_e32 v7, 16, v3
	v_lshlrev_b32_e32 v6, 16, v2
	v_pk_fma_f32 v[4:5], v[42:43], v[4:5], v[8:9] op_sel_hi:[0,1,1]
	v_mov_b32_e32 v14, v13
	v_and_b32_e32 v3, 0xffff0000, v3
	v_and_b32_e32 v2, 0xffff0000, v2
	v_pk_mul_f32 v[4:5], v[4:5], v[6:7]
	v_pk_fma_f32 v[0:1], v[42:43], v[0:1], v[14:15] op_sel_hi:[0,1,1]
	v_pk_mul_f32 v[0:1], v[0:1], v[2:3]
	v_and_b32_sdwa v2, v5, v159 dst_sel:DWORD dst_unused:UNUSED_PAD src0_sel:WORD_1 src1_sel:DWORD
	v_and_b32_sdwa v3, v4, v159 dst_sel:DWORD dst_unused:UNUSED_PAD src0_sel:WORD_1 src1_sel:DWORD
	v_add3_u32 v3, v4, v3, s50
	v_add3_u32 v2, v5, v2, s50
	v_and_b32_sdwa v4, v1, v159 dst_sel:DWORD dst_unused:UNUSED_PAD src0_sel:WORD_1 src1_sel:DWORD
	v_and_b32_sdwa v5, v0, v159 dst_sel:DWORD dst_unused:UNUSED_PAD src0_sel:WORD_1 src1_sel:DWORD
	v_add3_u32 v1, v1, v4, s50
	v_add3_u32 v0, v0, v5, s50
	v_and_b32_e32 v1, 0xffff0000, v1
	v_and_b32_e32 v0, 0xffff0000, v0
	v_or_b32_sdwa v1, v1, v2 dst_sel:DWORD dst_unused:UNUSED_PAD src0_sel:DWORD src1_sel:WORD_1
	v_or_b32_sdwa v0, v0, v3 dst_sel:DWORD dst_unused:UNUSED_PAD src0_sel:DWORD src1_sel:WORD_1
	ds_write_b64 v50, v[0:1]
	v_add_u32_e32 v0, 0x880, v18
	s_waitcnt lgkmcnt(0)
	s_barrier
	ds_read2_b32 v[0:1], v0 offset1:1
	v_add_u32_e32 v2, 0x888, v18
	ds_read2_b32 v[2:3], v2 offset1:1
	ds_read_b128 v[4:7], v51
	v_add_u32_e32 v8, 0x8a0, v18
	v_add_u32_e32 v9, 0x8a8, v18
	v_add_u32_e32 v10, 0x8c0, v18
	ds_read2_b32 v[26:27], v8 offset1:1
	ds_read2_b32 v[28:29], v9 offset1:1
	ds_read2_b32 v[30:31], v10 offset1:1
	ds_read_b64 v[46:47], v25
	ds_read_b128 v[34:37], v51 offset:480
	s_waitcnt lgkmcnt(5)
	v_mfma_f32_32x32x16_bf16 v[0:15], v[0:3], v[4:7], 0
	ds_read_b128 v[38:41], v51 offset:32
	ds_read_b128 v[42:45], v51 offset:64
	v_add_u32_e32 v25, 0x8c8, v18
	ds_read2_b32 v[32:33], v25 offset1:1
	v_add_u32_e32 v25, 0x8e0, v18
	s_waitcnt lgkmcnt(2)
	v_mfma_f32_32x32x16_bf16 v[0:15], v[26:29], v[38:41], v[0:15]
	v_add_u32_e32 v28, 0x8e8, v18
	v_add_u32_e32 v38, 0x900, v18
	ds_read2_b32 v[26:27], v25 offset1:1
	ds_read2_b32 v[28:29], v28 offset1:1
	ds_read2_b32 v[38:39], v38 offset1:1
	v_add_u32_e32 v25, 0x908, v18
	s_waitcnt lgkmcnt(3)
	v_mfma_f32_32x32x16_bf16 v[0:15], v[30:33], v[42:45], v[0:15]
	ds_read_b128 v[30:33], v51 offset:96
	ds_read_b128 v[42:45], v51 offset:128
	ds_read2_b32 v[40:41], v25 offset1:1
	v_add_u32_e32 v25, 0x920, v18
	s_waitcnt lgkmcnt(2)
	v_mfma_f32_32x32x16_bf16 v[0:15], v[26:29], v[30:33], v[0:15]
	v_add_u32_e32 v28, 0x928, v18
	v_add_u32_e32 v30, 0x940, v18
	ds_read2_b32 v[26:27], v25 offset1:1
	ds_read2_b32 v[28:29], v28 offset1:1
	ds_read2_b32 v[30:31], v30 offset1:1
	v_add_u32_e32 v25, 0x948, v18
	s_waitcnt lgkmcnt(3)
	v_mfma_f32_32x32x16_bf16 v[0:15], v[38:41], v[42:45], v[0:15]
	ds_read_b128 v[38:41], v51 offset:160
	ds_read_b128 v[42:45], v51 offset:192
	ds_read2_b32 v[32:33], v25 offset1:1
	v_add_u32_e32 v25, 0x960, v18
	s_waitcnt lgkmcnt(2)
	v_mfma_f32_32x32x16_bf16 v[0:15], v[26:29], v[38:41], v[0:15]
	v_add_u32_e32 v28, 0x968, v18
	v_add_u32_e32 v38, 0x980, v18
	ds_read2_b32 v[26:27], v25 offset1:1
	ds_read2_b32 v[28:29], v28 offset1:1
	ds_read2_b32 v[38:39], v38 offset1:1
	v_add_u32_e32 v25, 0x988, v18
	s_waitcnt lgkmcnt(3)
	v_mfma_f32_32x32x16_bf16 v[0:15], v[30:33], v[42:45], v[0:15]
	ds_read_b128 v[30:33], v51 offset:224
	ds_read_b128 v[42:45], v51 offset:256
	ds_read2_b32 v[40:41], v25 offset1:1
	v_add_u32_e32 v25, 0x9a0, v18
	s_waitcnt lgkmcnt(2)
	v_mfma_f32_32x32x16_bf16 v[0:15], v[26:29], v[30:33], v[0:15]
	v_add_u32_e32 v28, 0x9a8, v18
	v_add_u32_e32 v30, 0x9c0, v18
	ds_read2_b32 v[26:27], v25 offset1:1
	ds_read2_b32 v[28:29], v28 offset1:1
	ds_read2_b32 v[30:31], v30 offset1:1
	v_add_u32_e32 v25, 0x9c8, v18
	s_waitcnt lgkmcnt(3)
	v_mfma_f32_32x32x16_bf16 v[0:15], v[38:41], v[42:45], v[0:15]
	ds_read_b128 v[38:41], v51 offset:288
	ds_read_b128 v[42:45], v51 offset:320
	ds_read2_b32 v[32:33], v25 offset1:1
	v_add_u32_e32 v25, 0x9e0, v18
	s_waitcnt lgkmcnt(2)
	v_mfma_f32_32x32x16_bf16 v[0:15], v[26:29], v[38:41], v[0:15]
	v_add_u32_e32 v28, 0x9e8, v18
	v_add_u32_e32 v38, 0xa00, v18
	ds_read2_b32 v[26:27], v25 offset1:1
	ds_read2_b32 v[28:29], v28 offset1:1
	ds_read2_b32 v[38:39], v38 offset1:1
	v_add_u32_e32 v25, 0xa08, v18
	s_waitcnt lgkmcnt(3)
	v_mfma_f32_32x32x16_bf16 v[0:15], v[30:33], v[42:45], v[0:15]
	ds_read_b128 v[30:33], v51 offset:352
	ds_read_b128 v[42:45], v51 offset:384
	ds_read2_b32 v[40:41], v25 offset1:1
	v_add_u32_e32 v25, 0xa20, v18
	s_waitcnt lgkmcnt(2)
	v_mfma_f32_32x32x16_bf16 v[0:15], v[26:29], v[30:33], v[0:15]
	v_add_u32_e32 v28, 0xa28, v18
	v_add_u32_e32 v30, 0xa40, v18
	ds_read2_b32 v[26:27], v25 offset1:1
	ds_read2_b32 v[28:29], v28 offset1:1
	ds_read2_b32 v[30:31], v30 offset1:1
	v_add_u32_e32 v25, 0xa48, v18
	s_waitcnt lgkmcnt(3)
	v_mfma_f32_32x32x16_bf16 v[0:15], v[38:41], v[42:45], v[0:15]
	ds_read_b128 v[38:41], v51 offset:416
	ds_read_b128 v[42:45], v51 offset:448
	ds_read2_b32 v[32:33], v25 offset1:1
	v_add_u32_e32 v25, 0xa60, v18
	v_add_u32_e32 v18, 0xa68, v18
	s_waitcnt lgkmcnt(2)
	v_mfma_f32_32x32x16_bf16 v[0:15], v[26:29], v[38:41], v[0:15]
	v_add_u32_e32 v38, 0x1ca00, v19
	ds_read2_b32 v[26:27], v25 offset1:1
	ds_read2_b32 v[28:29], v18 offset1:1
	ds_read_b64 v[38:39], v38
	global_load_dword v18, v147, s[6:7]
	s_add_u32 s6, s2, s0
	s_addc_u32 s7, s3, s1
	s_waitcnt lgkmcnt(3)
	v_mfma_f32_32x32x16_bf16 v[0:15], v[30:33], v[42:45], v[0:15]
	s_waitcnt lgkmcnt(0)
	v_lshlrev_b32_e32 v31, 16, v39
	v_lshlrev_b32_e32 v30, 16, v38
	v_and_b32_e32 v33, 0xffff0000, v39
	v_and_b32_e32 v32, 0xffff0000, v38
	v_mfma_f32_32x32x16_bf16 v[0:15], v[26:29], v[34:37], v[0:15]
	v_lshlrev_b32_e32 v27, 16, v47
	v_lshlrev_b32_e32 v26, 16, v46
	v_and_b32_e32 v29, 0xffff0000, v47
	v_and_b32_e32 v28, 0xffff0000, v46
	s_nop 7
	v_mov_b32_e32 v34, v0
	v_mov_b32_e32 v35, v2
	v_mov_b32_e32 v2, v1
	s_waitcnt vmcnt(0)
	v_pk_fma_f32 v[26:27], v[18:19], v[26:27], v[34:35] op_sel_hi:[0,1,1]
	v_pk_mul_f32 v[26:27], v[26:27], v[30:31]
	v_pk_fma_f32 v[0:1], v[18:19], v[28:29], v[2:3] op_sel_hi:[0,1,1]
	v_pk_mul_f32 v[0:1], v[0:1], v[32:33]
	v_and_b32_sdwa v3, v26, v159 dst_sel:DWORD dst_unused:UNUSED_PAD src0_sel:WORD_1 src1_sel:DWORD
	v_add3_u32 v3, v26, v3, s50
	v_and_b32_sdwa v25, v1, v159 dst_sel:DWORD dst_unused:UNUSED_PAD src0_sel:WORD_1 src1_sel:DWORD
	v_and_b32_sdwa v26, v0, v159 dst_sel:DWORD dst_unused:UNUSED_PAD src0_sel:WORD_1 src1_sel:DWORD
	v_and_b32_sdwa v2, v27, v159 dst_sel:DWORD dst_unused:UNUSED_PAD src0_sel:WORD_1 src1_sel:DWORD
	v_add3_u32 v1, v1, v25, s50
	v_add3_u32 v0, v0, v26, s50
	v_add3_u32 v2, v27, v2, s50
	v_and_b32_e32 v1, 0xffff0000, v1
	v_and_b32_e32 v0, 0xffff0000, v0
	v_or_b32_sdwa v1, v1, v2 dst_sel:DWORD dst_unused:UNUSED_PAD src0_sel:DWORD src1_sel:WORD_1
	v_or_b32_sdwa v0, v0, v3 dst_sel:DWORD dst_unused:UNUSED_PAD src0_sel:DWORD src1_sel:WORD_1
	ds_write_b64 v20, v[0:1]
	ds_read_b64 v[0:1], v48
	v_add_u32_e32 v2, 0x1ca10, v19
	ds_read_b64 v[2:3], v2
	v_mov_b32_e32 v31, v6
	v_mov_b32_e32 v6, v5
	s_waitcnt lgkmcnt(1)
	v_lshlrev_b32_e32 v27, 16, v1
	v_lshlrev_b32_e32 v26, 16, v0
	v_and_b32_e32 v1, 0xffff0000, v1
	v_and_b32_e32 v0, 0xffff0000, v0
	s_waitcnt lgkmcnt(0)
	v_lshlrev_b32_e32 v29, 16, v3
	v_lshlrev_b32_e32 v28, 16, v2
	v_and_b32_e32 v3, 0xffff0000, v3
	v_and_b32_e32 v2, 0xffff0000, v2
	v_mov_b32_e32 v30, v4
	v_pk_fma_f32 v[0:1], v[18:19], v[0:1], v[6:7] op_sel_hi:[0,1,1]
	v_pk_fma_f32 v[26:27], v[18:19], v[26:27], v[30:31] op_sel_hi:[0,1,1]
	v_pk_mul_f32 v[0:1], v[0:1], v[2:3]
	v_pk_mul_f32 v[26:27], v[26:27], v[28:29]
	v_and_b32_sdwa v4, v1, v159 dst_sel:DWORD dst_unused:UNUSED_PAD src0_sel:WORD_1 src1_sel:DWORD
	v_and_b32_sdwa v5, v0, v159 dst_sel:DWORD dst_unused:UNUSED_PAD src0_sel:WORD_1 src1_sel:DWORD
	v_and_b32_sdwa v2, v27, v159 dst_sel:DWORD dst_unused:UNUSED_PAD src0_sel:WORD_1 src1_sel:DWORD
	v_and_b32_sdwa v3, v26, v159 dst_sel:DWORD dst_unused:UNUSED_PAD src0_sel:WORD_1 src1_sel:DWORD
	v_add3_u32 v1, v1, v4, s50
	v_add3_u32 v0, v0, v5, s50
	v_add3_u32 v3, v26, v3, s50
	v_add3_u32 v2, v27, v2, s50
	v_and_b32_e32 v1, 0xffff0000, v1
	v_and_b32_e32 v0, 0xffff0000, v0
	v_or_b32_sdwa v1, v1, v2 dst_sel:DWORD dst_unused:UNUSED_PAD src0_sel:DWORD src1_sel:WORD_1
	v_or_b32_sdwa v0, v0, v3 dst_sel:DWORD dst_unused:UNUSED_PAD src0_sel:DWORD src1_sel:WORD_1
	ds_write_b64 v21, v[0:1]
	ds_read_b64 v[0:1], v49
	v_add_u32_e32 v2, 0x1ca20, v19
	ds_read_b64 v[2:3], v2
	v_mov_b32_e32 v20, v8
	v_mov_b32_e32 v21, v10
	s_waitcnt lgkmcnt(1)
	v_lshlrev_b32_e32 v5, 16, v1
	v_lshlrev_b32_e32 v4, 16, v0
	v_and_b32_e32 v1, 0xffff0000, v1
	v_and_b32_e32 v0, 0xffff0000, v0
	s_waitcnt lgkmcnt(0)
	v_lshlrev_b32_e32 v7, 16, v3
	v_lshlrev_b32_e32 v6, 16, v2
	v_pk_fma_f32 v[4:5], v[18:19], v[4:5], v[20:21] op_sel_hi:[0,1,1]
	v_mov_b32_e32 v10, v9
	v_and_b32_e32 v3, 0xffff0000, v3
	v_and_b32_e32 v2, 0xffff0000, v2
	v_pk_mul_f32 v[4:5], v[4:5], v[6:7]
	v_pk_fma_f32 v[0:1], v[18:19], v[0:1], v[10:11] op_sel_hi:[0,1,1]
	v_pk_mul_f32 v[0:1], v[0:1], v[2:3]
	v_and_b32_sdwa v2, v5, v159 dst_sel:DWORD dst_unused:UNUSED_PAD src0_sel:WORD_1 src1_sel:DWORD
	v_and_b32_sdwa v3, v4, v159 dst_sel:DWORD dst_unused:UNUSED_PAD src0_sel:WORD_1 src1_sel:DWORD
	v_add3_u32 v3, v4, v3, s50
	v_add3_u32 v2, v5, v2, s50
	v_and_b32_sdwa v4, v1, v159 dst_sel:DWORD dst_unused:UNUSED_PAD src0_sel:WORD_1 src1_sel:DWORD
	v_and_b32_sdwa v5, v0, v159 dst_sel:DWORD dst_unused:UNUSED_PAD src0_sel:WORD_1 src1_sel:DWORD
	v_add3_u32 v1, v1, v4, s50
	v_add3_u32 v0, v0, v5, s50
	v_and_b32_e32 v1, 0xffff0000, v1
	v_and_b32_e32 v0, 0xffff0000, v0
	v_or_b32_sdwa v1, v1, v2 dst_sel:DWORD dst_unused:UNUSED_PAD src0_sel:DWORD src1_sel:WORD_1
	v_or_b32_sdwa v0, v0, v3 dst_sel:DWORD dst_unused:UNUSED_PAD src0_sel:DWORD src1_sel:WORD_1
	ds_write_b64 v22, v[0:1]
	ds_read_b64 v[0:1], v50
	v_add_u32_e32 v2, 0x1ca30, v19
	ds_read_b64 v[2:3], v2
	v_mov_b32_e32 v8, v12
	v_mov_b32_e32 v9, v14
	s_waitcnt lgkmcnt(1)
	v_lshlrev_b32_e32 v5, 16, v1
	v_lshlrev_b32_e32 v4, 16, v0
	v_and_b32_e32 v1, 0xffff0000, v1
	v_and_b32_e32 v0, 0xffff0000, v0
	s_waitcnt lgkmcnt(0)
	v_lshlrev_b32_e32 v7, 16, v3
	v_lshlrev_b32_e32 v6, 16, v2
	v_pk_fma_f32 v[4:5], v[18:19], v[4:5], v[8:9] op_sel_hi:[0,1,1]
	v_mov_b32_e32 v14, v13
	v_and_b32_e32 v3, 0xffff0000, v3
	v_and_b32_e32 v2, 0xffff0000, v2
	v_pk_mul_f32 v[4:5], v[4:5], v[6:7]
	v_pk_fma_f32 v[0:1], v[18:19], v[0:1], v[14:15] op_sel_hi:[0,1,1]
	v_pk_mul_f32 v[0:1], v[0:1], v[2:3]
	v_and_b32_sdwa v2, v5, v159 dst_sel:DWORD dst_unused:UNUSED_PAD src0_sel:WORD_1 src1_sel:DWORD
	v_and_b32_sdwa v3, v4, v159 dst_sel:DWORD dst_unused:UNUSED_PAD src0_sel:WORD_1 src1_sel:DWORD
	v_add3_u32 v3, v4, v3, s50
	v_add3_u32 v2, v5, v2, s50
	v_and_b32_sdwa v4, v1, v159 dst_sel:DWORD dst_unused:UNUSED_PAD src0_sel:WORD_1 src1_sel:DWORD
	v_and_b32_sdwa v5, v0, v159 dst_sel:DWORD dst_unused:UNUSED_PAD src0_sel:WORD_1 src1_sel:DWORD
	v_add3_u32 v1, v1, v4, s50
	v_add3_u32 v0, v0, v5, s50
	v_and_b32_e32 v1, 0xffff0000, v1
	v_and_b32_e32 v0, 0xffff0000, v0
	v_or_b32_sdwa v1, v1, v2 dst_sel:DWORD dst_unused:UNUSED_PAD src0_sel:DWORD src1_sel:WORD_1
	v_or_b32_sdwa v0, v0, v3 dst_sel:DWORD dst_unused:UNUSED_PAD src0_sel:DWORD src1_sel:WORD_1
	ds_write_b64 v23, v[0:1]
	s_waitcnt lgkmcnt(0)
	s_barrier
	ds_read_b128 v[2:5], v24
	v_lshl_add_u64 v[0:1], v[16:17], 1, s[6:7]
	s_mov_b64 s[6:7], 0
	s_waitcnt lgkmcnt(0)
	global_store_dwordx4 v[0:1], v[2:5], off

.LBB0_1871:
	s_or_b64 exec, exec, s[6:7]
	v_cmp_gt_i32_e32 vcc, s51, v12
	s_and_saveexec_b64 s[6:7], vcc
	v_lshl_add_u32 v0, v12, 2, v158
	ds_write_b32 v0, v147
	s_or_b64 exec, exec, s[6:7]
	s_lshl_b64 s[6:7], s[36:37], 15
	s_add_u32 s6, s86, s6
	v_lshlrev_b32_e32 v144, 4, v12
	s_addc_u32 s7, s87, s7
	v_ashrrev_i32_e32 v145, 31, v144
	v_lshl_add_u64 v[2:3], v[144:145], 1, s[6:7]
	v_lshl_add_u64 v[0:1], v[2:3], 0, s[26:27]
	v_add_co_u32_e32 v2, vcc, 0x4000, v2
	v_and_b32_e32 v10, 0xff0, v144
	s_nop 0
	v_addc_co_u32_e32 v3, vcc, 0, v3, vcc
	global_load_dwordx4 v[6:9], v[2:3], off
	s_nop 0
	global_load_dwordx4 v[2:5], v[0:1], off offset:16
	v_cmp_ne_u32_e64 s[2:3], 0, v10
	v_mov_b32_e32 v11, 0
	v_mov_b32_e32 v17, 0
	v_mov_b32_e32 v232, 0
	s_and_saveexec_b64 s[8:9], s[2:3]
	s_cbranch_execz .LBB0_1875
	global_load_ushort v232, v[0:1], off offset:-2
.LBB0_1875:
	s_or_b64 exec, exec, s[8:9]
	v_cmp_ne_u32_e64 s[0:1], s66, v10
	v_mov_b32_e32 v233, 0
	s_and_saveexec_b64 s[10:11], s[0:1]
	s_cbranch_execz .LBB0_1877
	global_load_ushort v233, v[0:1], off offset:32
.LBB0_1877:
	s_or_b64 exec, exec, s[10:11]
	v_readlane_b32 s8, v241, 35
	s_lshl_b64 s[4:5], s[36:37], 2
	v_readlane_b32 s12, v241, 39
	v_readlane_b32 s14, v241, 41
	v_readlane_b32 s13, v241, 40
	v_readlane_b32 s15, v241, 42
	s_add_u32 s12, s14, s4
	v_readlane_b32 s10, v241, 37
	v_readlane_b32 s16, v241, 43
	s_addc_u32 s13, s15, s5
	v_readlane_b32 s11, v241, 38
	v_readlane_b32 s17, v241, 44
	global_load_dword v15, v147, s[12:13]
	global_load_dword v14, v152, s[12:13]
	global_load_dword v20, v153, s[12:13]
	s_add_u32 s10, s16, s4
	s_addc_u32 s11, s17, s5
	global_load_dword v22, v147, s[10:11]
	v_readlane_b32 s20, v241, 47
	v_readlane_b32 s21, v241, 48
	s_lshl_b64 s[20:21], s[30:31], 15
	s_add_u32 s12, s86, s20
	s_waitcnt vmcnt(4)
	v_lshlrev_b32_e32 v17, 16, v232
	v_lshlrev_b32_e32 v11, 16, v233
	v_pk_mov_b32 v[0:1], v[8:9], v[2:3] op_sel:[1,0]
	s_addc_u32 s13, s87, s21
	v_and_b32_e32 v45, 0xffff0000, v1
	v_and_b32_e32 v44, 0xffff0000, v0
	v_lshl_add_u64 v[0:1], v[144:145], 1, s[12:13]
	v_lshlrev_b32_e32 v32, 16, v6
	v_and_b32_e32 v34, 0xffff0000, v6
	v_add_co_u32_e32 v6, vcc, 0x4000, v0
	v_lshlrev_b32_e32 v28, 16, v7
	v_and_b32_e32 v35, 0xffff0000, v7
	v_lshl_add_u64 v[18:19], v[0:1], 0, s[26:27]
	v_addc_co_u32_e32 v7, vcc, 0, v1, vcc
	v_lshlrev_b32_e32 v27, 16, v9
	v_and_b32_e32 v26, 0xffff0000, v8
	v_lshlrev_b32_e32 v29, 16, v8
	v_lshlrev_b32_e32 v36, 16, v3
	v_lshlrev_b32_e32 v38, 16, v2
	v_and_b32_e32 v41, 0xffff0000, v3
	v_and_b32_e32 v40, 0xffff0000, v2
	global_load_dwordx4 v[0:3], v[18:19], off offset:16
	s_nop 0
	global_load_dwordx4 v[6:9], v[6:7], off
	v_mov_b32_e32 v16, v28
	v_mov_b32_e32 v39, v36
	v_mov_b32_e32 v48, v29
	v_mov_b32_e32 v49, v27
	v_mov_b32_e32 v33, v28
	v_mov_b32_e32 v42, v32
	v_mov_b32_e32 v43, v34
	v_pk_mov_b32 v[46:47], v[34:35], v[26:27] op_sel:[1,0]
	v_lshlrev_b32_e32 v37, 16, v4
	v_mov_b32_e32 v50, v26
	v_mov_b32_e32 v51, v44
	v_pk_mov_b32 v[52:53], v[26:27], v[38:39] op_sel:[1,0]
	v_lshlrev_b32_e32 v31, 16, v5
	v_and_b32_e32 v5, 0xffff0000, v5
	v_and_b32_e32 v4, 0xffff0000, v4
	v_readlane_b32 s9, v241, 36
	v_readlane_b32 s18, v241, 45
	v_readlane_b32 s19, v241, 46
	v_readlane_b32 s22, v241, 49
	v_readlane_b32 s23, v241, 50
	s_waitcnt vmcnt(5)
	v_mov_b32_e32 v24, v15
	s_waitcnt vmcnt(4)
	v_pk_mul_f32 v[16:17], v[16:17], v[14:15]
	v_pk_mul_f32 v[54:55], v[14:15], v[34:35] op_sel_hi:[0,1]
	v_pk_mul_f32 v[56:57], v[14:15], v[38:39] op_sel_hi:[0,1]
	v_pk_mul_f32 v[58:59], v[14:15], v[40:41] op_sel_hi:[0,1]
	v_pk_mul_f32 v[48:49], v[14:15], v[48:49] op_sel_hi:[0,1]
	v_pk_fma_f32 v[16:17], v[14:15], v[42:43], v[16:17] op_sel:[0,0,1] op_sel_hi:[1,1,0]
	v_pk_fma_f32 v[32:33], v[24:25], v[32:33], v[54:55] op_sel_hi:[0,1,1]
	v_pk_fma_f32 v[42:43], v[24:25], v[44:45], v[56:57] op_sel_hi:[0,1,1]
	v_pk_fma_f32 v[38:39], v[24:25], v[38:39], v[58:59] op_sel_hi:[0,1,1]
	v_pk_fma_f32 v[46:47], v[24:25], v[46:47], v[48:49] op_sel_hi:[0,1,1]
	v_mov_b32_e32 v45, v29
	s_waitcnt vmcnt(3)
	v_pk_fma_f32 v[16:17], v[20:21], v[34:35], v[16:17] op_sel_hi:[0,1,1]
	v_pk_fma_f32 v[28:29], v[20:21], v[28:29], v[32:33] op_sel_hi:[0,1,1]
	v_pk_fma_f32 v[32:33], v[20:21], v[40:41], v[42:43] op_sel_hi:[0,1,1]
	v_pk_fma_f32 v[34:35], v[20:21], v[36:37], v[38:39] op_sel_hi:[0,1,1]
	v_pk_fma_f32 v[38:39], v[20:21], v[50:51], v[46:47] op_sel_hi:[0,1,1]
	v_pk_mul_f32 v[42:43], v[14:15], v[44:45]
	s_waitcnt vmcnt(2)
	v_pk_add_f32 v[16:17], v[22:23], v[16:17] op_sel_hi:[0,1]
	v_pk_add_f32 v[38:39], v[22:23], v[38:39] op_sel_hi:[0,1]
	v_pk_fma_f32 v[26:27], v[14:15], v[26:27], v[42:43] op_sel:[0,0,1] op_sel_hi:[1,1,0]
	v_pk_add_f32 v[28:29], v[22:23], v[28:29] op_sel_hi:[0,1]
	v_pk_add_f32 v[32:33], v[22:23], v[32:33] op_sel_hi:[0,1]
	v_pk_add_f32 v[34:35], v[22:23], v[34:35] op_sel_hi:[0,1]
	v_pk_fma_f32 v[26:27], v[20:21], v[52:53], v[26:27] op_sel_hi:[0,1,1]
	v_bfe_u32 v23, v38, 16, 1
	v_bfe_u32 v36, v16, 16, 1
	v_bfe_u32 v42, v17, 16, 1
	v_bfe_u32 v10, v29, 16, 1
	v_bfe_u32 v21, v28, 16, 1
	v_bfe_u32 v30, v39, 16, 1
	v_pk_add_f32 v[26:27], v[22:23], v[26:27] op_sel_hi:[0,1]
	v_add3_u32 v17, v17, v42, s50
	v_add3_u32 v16, v16, v36, s50
	v_add3_u32 v21, v28, v21, s50
	v_add3_u32 v10, v29, v10, s50
	v_add3_u32 v28, v39, v30, s50
	v_add3_u32 v23, v38, v23, s50
	v_bfe_u32 v29, v27, 16, 1
	v_bfe_u32 v30, v26, 16, 1
	v_lshrrev_b32_e32 v16, 16, v16
	v_lshrrev_b32_e32 v17, 16, v17
	v_mov_b32_e32 v38, v37
	v_mov_b32_e32 v39, v31
	v_add3_u32 v30, v26, v30, s50
	v_add3_u32 v29, v27, v29, s50
	v_and_or_b32 v27, v10, s52, v17
	v_and_or_b32 v26, v21, s52, v16
	v_pk_mov_b32 v[16:17], v[40:41], v[4:5] op_sel:[1,0]
	v_pk_mul_f32 v[38:39], v[14:15], v[38:39] op_sel_hi:[0,1]
	v_lshrrev_b32_e32 v23, 16, v23
	v_lshrrev_b32_e32 v28, 16, v28
	v_pk_fma_f32 v[16:17], v[24:25], v[16:17], v[38:39] op_sel_hi:[0,1,1]
	v_mov_b32_e32 v36, v5
	v_and_or_b32 v29, v29, s52, v28
	v_and_or_b32 v28, v30, s52, v23
	v_mov_b32_e32 v30, v4
	v_pk_fma_f32 v[16:17], v[20:21], v[4:5], v[16:17] op_sel_hi:[0,1,1]
	v_pk_mul_f32 v[4:5], v[14:15], v[36:37]
	v_mov_b32_e32 v10, v31
	v_pk_fma_f32 v[4:5], v[14:15], v[30:31], v[4:5] op_sel:[0,0,1] op_sel_hi:[1,1,0]
	v_pk_add_f32 v[16:17], v[22:23], v[16:17] op_sel_hi:[0,1]
	v_pk_fma_f32 v[4:5], v[20:21], v[10:11], v[4:5] op_sel_hi:[0,1,1]
	v_pk_add_f32 v[4:5], v[22:23], v[4:5] op_sel_hi:[0,1]
	v_bfe_u32 v14, v5, 16, 1
	v_bfe_u32 v15, v4, 16, 1
	v_add3_u32 v5, v5, v14, s50
	v_bfe_u32 v14, v16, 16, 1
	v_add3_u32 v4, v4, v15, s50
	v_bfe_u32 v15, v17, 16, 1
	v_bfe_u32 v20, v32, 16, 1
	v_bfe_u32 v21, v33, 16, 1
	v_add3_u32 v14, v16, v14, s50
	v_add3_u32 v15, v17, v15, s50
	v_add3_u32 v16, v33, v21, s50
	v_add3_u32 v17, v32, v20, s50
	v_lshrrev_b32_e32 v20, 16, v14
	v_lshrrev_b32_e32 v21, 16, v15
	v_lshrrev_b32_e32 v15, 16, v16
	v_and_or_b32 v16, v4, s52, v20
	v_ashrrev_i32_e32 v4, 4, v12
	v_mul_lo_u32 v4, v4, s53
	v_bfe_u32 v10, v35, 16, 1
	v_lshlrev_b32_e32 v20, 1, v4
	v_and_b32_e32 v4, 0xf0, v144
	v_bfe_u32 v11, v34, 16, 1
	v_add3_u32 v10, v35, v10, s50
	v_lshrrev_b32_e32 v14, 16, v17
	v_and_or_b32 v17, v5, s52, v21
	v_lshlrev_b32_e32 v21, 1, v4
	v_add3_u32 v11, v34, v11, s50
	v_and_or_b32 v15, v10, s52, v15
	v_add3_u32 v161, v20, v21, s54
	v_and_or_b32 v14, v11, s52, v14
	ds_write_b128 v161, v[26:29]
	ds_write_b128 v161, v[14:17] offset:16
	v_mov_b32_e32 v15, 0
	v_mov_b32_e32 v17, 0
	v_mov_b32_e32 v234, 0
	s_and_saveexec_b64 s[12:13], s[2:3]
	s_cbranch_execz .LBB0_1879
	global_load_ushort v234, v[18:19], off offset:-2
.LBB0_1879:
	s_or_b64 exec, exec, s[12:13]
	v_mov_b32_e32 v235, 0
	s_and_saveexec_b64 s[12:13], s[0:1]
	s_cbranch_execz .LBB0_1881
	global_load_ushort v235, v[18:19], off offset:32
.LBB0_1881:
	s_or_b64 exec, exec, s[12:13]
	v_readlane_b32 s4, v241, 35
	s_lshl_b64 s[22:23], s[30:31], 2
	v_readlane_b32 s10, v241, 41
	v_readlane_b32 s14, v241, 45
	v_readlane_b32 s11, v241, 42
	v_readlane_b32 s15, v241, 46
	s_add_u32 s14, s10, s22
	v_readlane_b32 s12, v241, 43
	v_readlane_b32 s16, v241, 47
	s_addc_u32 s15, s11, s23
	v_readlane_b32 s13, v241, 44
	v_readlane_b32 s17, v241, 48
	global_load_dword v23, v147, s[14:15]
	global_load_dword v22, v152, s[14:15]
	global_load_dword v24, v153, s[14:15]
	s_add_u32 s16, s12, s22
	s_addc_u32 s17, s13, s23
	global_load_dword v30, v147, s[16:17]
	v_readlane_b32 s18, v241, 49
	v_readlane_b32 s19, v241, 50
	s_lshl_b64 s[18:19], s[34:35], 15
	s_add_u32 s18, s86, s18
	s_addc_u32 s19, s87, s19
	v_lshl_add_u64 v[4:5], v[144:145], 1, s[18:19]
	s_waitcnt vmcnt(4)
	v_lshlrev_b32_e32 v17, 16, v234
	v_lshlrev_b32_e32 v15, 16, v235
	v_and_b32_e32 v26, 0xffff0000, v8
	v_lshlrev_b32_e32 v29, 16, v8
	v_lshlrev_b32_e32 v38, 16, v1
	v_lshlrev_b32_e32 v40, 16, v0
	v_and_b32_e32 v43, 0xffff0000, v1
	v_and_b32_e32 v42, 0xffff0000, v0
	v_pk_mov_b32 v[0:1], v[8:9], v[0:1] op_sel:[1,0]
	v_add_co_u32_e32 v8, vcc, 0x4000, v4
	v_lshlrev_b32_e32 v27, 16, v9
	v_lshl_add_u64 v[18:19], v[4:5], 0, s[26:27]
	v_addc_co_u32_e32 v9, vcc, 0, v5, vcc
	v_lshlrev_b32_e32 v28, 16, v7
	v_lshlrev_b32_e32 v34, 16, v6
	v_and_b32_e32 v37, 0xffff0000, v7
	v_and_b32_e32 v36, 0xffff0000, v6
	global_load_dwordx4 v[4:7], v[18:19], off offset:16
	s_nop 0
	global_load_dwordx4 v[8:11], v[8:9], off
	v_mov_b32_e32 v16, v28
	v_mov_b32_e32 v41, v38
	v_mov_b32_e32 v48, v29
	v_mov_b32_e32 v49, v27
	v_mov_b32_e32 v44, v34
	v_mov_b32_e32 v45, v36
	v_and_b32_e32 v1, 0xffff0000, v1
	v_and_b32_e32 v0, 0xffff0000, v0
	v_pk_mov_b32 v[46:47], v[36:37], v[26:27] op_sel:[1,0]
	v_lshlrev_b32_e32 v39, 16, v2
	v_mov_b32_e32 v35, v28
	v_mov_b32_e32 v50, v26
	v_mov_b32_e32 v51, v0
	v_pk_mov_b32 v[52:53], v[26:27], v[40:41] op_sel:[1,0]
	v_lshlrev_b32_e32 v33, 16, v3
	v_readlane_b32 s5, v241, 36
	v_readlane_b32 s6, v241, 37
	v_readlane_b32 s7, v241, 38
	v_readlane_b32 s8, v241, 39
	v_readlane_b32 s9, v241, 40
	s_waitcnt vmcnt(5)
	v_mov_b32_e32 v56, v23
	s_waitcnt vmcnt(4)
	v_pk_mul_f32 v[16:17], v[16:17], v[22:23]
	v_pk_mul_f32 v[58:59], v[22:23], v[40:41] op_sel_hi:[0,1]
	v_pk_mul_f32 v[60:61], v[22:23], v[42:43] op_sel_hi:[0,1]
	v_pk_mul_f32 v[48:49], v[22:23], v[48:49] op_sel_hi:[0,1]
	v_pk_mul_f32 v[54:55], v[22:23], v[36:37] op_sel_hi:[0,1]
	v_pk_fma_f32 v[16:17], v[22:23], v[44:45], v[16:17] op_sel:[0,0,1] op_sel_hi:[1,1,0]
	v_pk_fma_f32 v[44:45], v[56:57], v[0:1], v[58:59] op_sel_hi:[0,1,1]
	v_pk_fma_f32 v[40:41], v[56:57], v[40:41], v[60:61] op_sel_hi:[0,1,1]
	v_pk_fma_f32 v[46:47], v[56:57], v[46:47], v[48:49] op_sel_hi:[0,1,1]
	v_mov_b32_e32 v1, v29
	v_pk_fma_f32 v[34:35], v[56:57], v[34:35], v[54:55] op_sel_hi:[0,1,1]
	s_waitcnt vmcnt(3)
	v_pk_fma_f32 v[16:17], v[24:25], v[36:37], v[16:17] op_sel_hi:[0,1,1]
	v_pk_fma_f32 v[36:37], v[24:25], v[38:39], v[40:41] op_sel_hi:[0,1,1]
	v_pk_fma_f32 v[40:41], v[24:25], v[50:51], v[46:47] op_sel_hi:[0,1,1]
	v_pk_mul_f32 v[0:1], v[22:23], v[0:1]
	v_pk_fma_f32 v[28:29], v[24:25], v[28:29], v[34:35] op_sel_hi:[0,1,1]
	v_pk_fma_f32 v[34:35], v[24:25], v[42:43], v[44:45] op_sel_hi:[0,1,1]
	s_waitcnt vmcnt(2)
	v_pk_add_f32 v[40:41], v[30:31], v[40:41] op_sel_hi:[0,1]
	v_pk_fma_f32 v[0:1], v[22:23], v[26:27], v[0:1] op_sel:[0,0,1] op_sel_hi:[1,1,0]
	v_pk_add_f32 v[16:17], v[30:31], v[16:17] op_sel_hi:[0,1]
	v_pk_add_f32 v[28:29], v[30:31], v[28:29] op_sel_hi:[0,1]
	v_pk_add_f32 v[34:35], v[30:31], v[34:35] op_sel_hi:[0,1]
	v_pk_add_f32 v[36:37], v[30:31], v[36:37] op_sel_hi:[0,1]
	v_pk_fma_f32 v[0:1], v[24:25], v[52:53], v[0:1] op_sel_hi:[0,1,1]
	v_bfe_u32 v31, v41, 16, 1
	v_bfe_u32 v14, v29, 16, 1
	v_bfe_u32 v26, v28, 16, 1
	v_bfe_u32 v27, v40, 16, 1
	v_bfe_u32 v32, v16, 16, 1
	v_bfe_u32 v38, v17, 16, 1
	v_pk_add_f32 v[0:1], v[30:31], v[0:1] op_sel_hi:[0,1]
	v_add3_u32 v26, v28, v26, s50
	v_add3_u32 v14, v29, v14, s50
	v_add3_u32 v17, v17, v38, s50
	v_add3_u32 v16, v16, v32, s50
	v_add3_u32 v28, v41, v31, s50
	v_add3_u32 v27, v40, v27, s50
	v_bfe_u32 v29, v1, 16, 1
	v_bfe_u32 v31, v0, 16, 1
	v_lshrrev_b32_e32 v32, 16, v27
	v_add3_u32 v0, v0, v31, s50
	v_add3_u32 v1, v1, v29, s50
	v_lshrrev_b32_e32 v28, 16, v28
	v_lshrrev_b32_e32 v16, 16, v16
	v_lshrrev_b32_e32 v17, 16, v17
	v_and_or_b32 v27, v14, s52, v17
	v_and_or_b32 v26, v26, s52, v16
	v_and_or_b32 v29, v1, s52, v28
	v_and_or_b32 v28, v0, s52, v32
	v_and_b32_e32 v1, 0xffff0000, v3
	v_and_b32_e32 v0, 0xffff0000, v2
	v_mov_b32_e32 v16, v39
	v_mov_b32_e32 v17, v33
	v_pk_mov_b32 v[2:3], v[42:43], v[0:1] op_sel:[1,0]
	v_pk_mul_f32 v[16:17], v[22:23], v[16:17] op_sel_hi:[0,1]
	v_pk_fma_f32 v[2:3], v[56:57], v[2:3], v[16:17] op_sel_hi:[0,1,1]
	v_mov_b32_e32 v38, v1
	v_mov_b32_e32 v32, v0
	v_pk_fma_f32 v[2:3], v[24:25], v[0:1], v[2:3] op_sel_hi:[0,1,1]
	v_pk_mul_f32 v[0:1], v[22:23], v[38:39]
	v_mov_b32_e32 v14, v33
	v_pk_fma_f32 v[0:1], v[22:23], v[32:33], v[0:1] op_sel:[0,0,1] op_sel_hi:[1,1,0]
	v_pk_add_f32 v[2:3], v[30:31], v[2:3] op_sel_hi:[0,1]
	v_pk_fma_f32 v[0:1], v[24:25], v[14:15], v[0:1] op_sel_hi:[0,1,1]
	v_pk_add_f32 v[0:1], v[30:31], v[0:1] op_sel_hi:[0,1]
	v_bfe_u32 v14, v37, 16, 1
	v_bfe_u32 v15, v36, 16, 1
	v_bfe_u32 v16, v1, 16, 1
	v_bfe_u32 v17, v0, 16, 1
	v_add3_u32 v17, v0, v17, s50
	v_add3_u32 v16, v1, v16, s50
	v_add3_u32 v0, v36, v15, s50
	v_add3_u32 v1, v37, v14, s50
	v_bfe_u32 v14, v2, 16, 1
	v_bfe_u32 v15, v3, 16, 1
	v_bfe_u32 v23, v35, 16, 1
	v_bfe_u32 v22, v34, 16, 1
	v_add3_u32 v3, v3, v15, s50
	v_add3_u32 v2, v2, v14, s50
	v_add3_u32 v14, v35, v23, s50
	v_add3_u32 v15, v34, v22, s50
	v_lshrrev_b32_e32 v3, 16, v3
	v_lshrrev_b32_e32 v14, 16, v14
	v_lshrrev_b32_e32 v2, 16, v2
	v_lshrrev_b32_e32 v15, 16, v15
	v_and_or_b32 v1, v1, s52, v14
	v_and_or_b32 v3, v16, s52, v3
	v_add3_u32 v14, v20, v21, s55
	v_and_or_b32 v0, v0, s52, v15
	v_and_or_b32 v2, v17, s52, v2
	ds_write_b128 v14, v[26:29]
	ds_write_b128 v14, v[0:3] offset:16
	v_mov_b32_e32 v1, 0
	v_mov_b32_e32 v3, 0
	v_mov_b32_e32 v236, 0
	s_and_saveexec_b64 s[18:19], s[2:3]
	s_cbranch_execz .LBB0_1883
	global_load_ushort v236, v[18:19], off offset:-2
.LBB0_1883:
	s_or_b64 exec, exec, s[18:19]
	v_mov_b32_e32 v237, 0
	s_and_saveexec_b64 s[6:7], s[0:1]
	s_cbranch_execz .LBB0_1885
	global_load_ushort v237, v[18:19], off offset:32
.LBB0_1885:
	s_or_b64 exec, exec, s[6:7]
	global_load_dword v15, v155, s[14:15]
	global_load_dword v14, v156, s[14:15]
	global_load_dword v16, v157, s[14:15]
	global_load_dword v18, v155, s[16:17]
	s_waitcnt vmcnt(4)
	v_lshlrev_b32_e32 v3, 16, v236
	v_lshlrev_b32_e32 v1, 16, v237
	v_lshlrev_b32_e32 v26, 16, v9
	v_and_b32_e32 v24, 0xffff0000, v10
	v_lshlrev_b32_e32 v27, 16, v10
	v_lshlrev_b32_e32 v10, 16, v8
	v_and_b32_e32 v8, 0xffff0000, v8
	v_lshlrev_b32_e32 v28, 16, v5
	v_mov_b32_e32 v2, v26
	v_lshrrev_b32_e32 v167, 5, v25
	v_lshlrev_b32_e32 v25, 16, v11
	v_and_b32_e32 v9, 0xffff0000, v9
	v_lshlrev_b32_e32 v30, 16, v4
	v_and_b32_e32 v33, 0xffff0000, v5
	v_and_b32_e32 v32, 0xffff0000, v4
	v_pk_mov_b32 v[4:5], v[10:11], v[4:5] op_sel:[1,0]
	v_mov_b32_e32 v34, v10
	v_mov_b32_e32 v35, v8
	v_mov_b32_e32 v31, v28
	v_and_b32_e32 v17, 31, v12
	v_mov_b32_e32 v11, v26
	v_and_b32_e32 v5, 0xffff0000, v5
	v_and_b32_e32 v4, 0xffff0000, v4
	v_mov_b32_e32 v38, v27
	v_mov_b32_e32 v39, v25
	v_pk_mov_b32 v[36:37], v[8:9], v[24:25] op_sel:[1,0]
	v_lshlrev_b32_e32 v23, 16, v7
	v_lshlrev_b32_e32 v29, 16, v6
	v_and_b32_e32 v7, 0xffff0000, v7
	v_and_b32_e32 v6, 0xffff0000, v6
	v_mov_b32_e32 v40, v24
	v_mov_b32_e32 v41, v4
	v_pk_mov_b32 v[46:47], v[24:25], v[30:31] op_sel:[1,0]
	v_pk_mov_b32 v[42:43], v[32:33], v[6:7] op_sel:[1,0]
	v_mov_b32_e32 v44, v29
	v_mov_b32_e32 v45, v23
	v_mov_b32_e32 v22, v6
	v_mov_b32_e32 v0, v23
	v_bitop3_b32 v85, v12, s76, 31 bitop3:0x6c
	v_lshlrev_b32_e32 v168, 5, v13
	v_lshlrev_b32_e32 v174, 3, v167
	v_bitop3_b32 v84, v12, 1, v12 bitop3:0xc
	v_mul_u32_u24_e32 v169, 0x108, v17
	v_lshlrev_b32_e32 v178, 1, v169
	v_add_u32_e32 v162, 16, v161
	s_mov_b32 s4, 0
	v_mul_u32_u24_e32 v163, 0x4040, v84
	s_waitcnt vmcnt(3)
	v_mov_b32_e32 v50, v15
	s_waitcnt vmcnt(2)
	v_pk_mul_f32 v[2:3], v[2:3], v[14:15]
	v_pk_mul_f32 v[48:49], v[14:15], v[8:9] op_sel_hi:[0,1]
	v_pk_mul_f32 v[52:53], v[14:15], v[30:31] op_sel_hi:[0,1]
	v_pk_fma_f32 v[2:3], v[14:15], v[34:35], v[2:3] op_sel:[0,0,1] op_sel_hi:[1,1,0]
	v_pk_mul_f32 v[54:55], v[14:15], v[32:33] op_sel_hi:[0,1]
	v_pk_mul_f32 v[38:39], v[14:15], v[38:39] op_sel_hi:[0,1]
	v_pk_fma_f32 v[10:11], v[50:51], v[10:11], v[48:49] op_sel_hi:[0,1,1]
	v_pk_fma_f32 v[34:35], v[50:51], v[4:5], v[52:53] op_sel_hi:[0,1,1]
	v_mov_b32_e32 v5, v27
	s_waitcnt vmcnt(1)
	v_pk_fma_f32 v[2:3], v[16:17], v[8:9], v[2:3] op_sel_hi:[0,1,1]
	v_pk_fma_f32 v[30:31], v[50:51], v[30:31], v[54:55] op_sel_hi:[0,1,1]
	v_pk_fma_f32 v[36:37], v[50:51], v[36:37], v[38:39] op_sel_hi:[0,1,1]
	v_pk_fma_f32 v[8:9], v[16:17], v[26:27], v[10:11] op_sel_hi:[0,1,1]
	v_pk_mul_f32 v[4:5], v[14:15], v[4:5]
	s_waitcnt vmcnt(0)
	v_pk_add_f32 v[2:3], v[18:19], v[2:3] op_sel_hi:[0,1]
	v_pk_fma_f32 v[10:11], v[16:17], v[32:33], v[34:35] op_sel_hi:[0,1,1]
	v_pk_fma_f32 v[26:27], v[16:17], v[28:29], v[30:31] op_sel_hi:[0,1,1]
	v_pk_fma_f32 v[30:31], v[16:17], v[40:41], v[36:37] op_sel_hi:[0,1,1]
	v_pk_add_f32 v[8:9], v[18:19], v[8:9] op_sel_hi:[0,1]
	v_pk_fma_f32 v[4:5], v[14:15], v[24:25], v[4:5] op_sel:[0,0,1] op_sel_hi:[1,1,0]
	v_bfe_u32 v32, v2, 16, 1
	v_bfe_u32 v33, v3, 16, 1
	v_pk_add_f32 v[10:11], v[18:19], v[10:11] op_sel_hi:[0,1]
	v_pk_add_f32 v[26:27], v[18:19], v[26:27] op_sel_hi:[0,1]
	v_pk_add_f32 v[30:31], v[18:19], v[30:31] op_sel_hi:[0,1]
	v_pk_fma_f32 v[4:5], v[16:17], v[46:47], v[4:5] op_sel_hi:[0,1,1]
	v_bfe_u32 v19, v9, 16, 1
	v_bfe_u32 v24, v8, 16, 1
	v_add3_u32 v3, v3, v33, s50
	v_add3_u32 v2, v2, v32, s50
	v_bfe_u32 v28, v31, 16, 1
	v_pk_add_f32 v[4:5], v[18:19], v[4:5] op_sel_hi:[0,1]
	v_add3_u32 v8, v8, v24, s50
	v_add3_u32 v9, v9, v19, s50
	v_lshrrev_b32_e32 v2, 16, v2
	v_lshrrev_b32_e32 v3, 16, v3
	v_add3_u32 v19, v31, v28, s50
	v_bfe_u32 v28, v4, 16, 1
	v_and_or_b32 v3, v9, s52, v3
	v_and_or_b32 v2, v8, s52, v2
	v_pk_mul_f32 v[8:9], v[14:15], v[44:45] op_sel_hi:[0,1]
	v_add3_u32 v4, v4, v28, s50
	v_pk_fma_f32 v[8:9], v[50:51], v[42:43], v[8:9] op_sel_hi:[0,1,1]
	v_mov_b32_e32 v28, v7
	v_pk_fma_f32 v[8:9], v[16:17], v[6:7], v[8:9] op_sel_hi:[0,1,1]
	v_pk_mul_f32 v[6:7], v[14:15], v[28:29]
	v_lshrrev_b32_e32 v19, 16, v19
	v_pk_fma_f32 v[6:7], v[14:15], v[22:23], v[6:7] op_sel:[0,0,1] op_sel_hi:[1,1,0]
	v_pk_add_f32 v[8:9], v[18:19], v[8:9] op_sel_hi:[0,1]
	v_pk_fma_f32 v[0:1], v[16:17], v[0:1], v[6:7] op_sel_hi:[0,1,1]
	v_pk_add_f32 v[0:1], v[18:19], v[0:1] op_sel_hi:[0,1]
	v_bfe_u32 v7, v26, 16, 1
	v_bfe_u32 v14, v1, 16, 1
	v_bfe_u32 v25, v30, 16, 1
	v_bfe_u32 v15, v0, 16, 1
	v_add3_u32 v1, v1, v14, s50
	v_add3_u32 v14, v26, v7, s50
	v_bfe_u32 v7, v8, 16, 1
	v_add3_u32 v24, v30, v25, s50
	v_bfe_u32 v25, v5, 16, 1
	v_add3_u32 v0, v0, v15, s50
	v_bfe_u32 v15, v9, 16, 1
	v_bfe_u32 v16, v10, 16, 1
	v_bfe_u32 v18, v11, 16, 1
	v_add3_u32 v7, v8, v7, s50
	v_lshrrev_b32_e32 v24, 16, v24
	v_add3_u32 v5, v5, v25, s50
	v_bfe_u32 v6, v27, 16, 1
	v_add3_u32 v9, v9, v15, s50
	v_add3_u32 v8, v11, v18, s50
	v_add3_u32 v10, v10, v16, s50
	v_lshrrev_b32_e32 v11, 16, v7
	v_and_or_b32 v5, v5, s52, v19
	v_and_or_b32 v4, v4, s52, v24
	v_add3_u32 v6, v27, v6, s50
	v_lshrrev_b32_e32 v9, 16, v9
	v_lshrrev_b32_e32 v10, 16, v10
	v_lshrrev_b32_e32 v7, 16, v8
	v_and_or_b32 v8, v0, s52, v11
	v_add3_u32 v0, v20, v21, s56
	v_and_or_b32 v7, v6, s52, v7
	v_and_or_b32 v6, v14, s52, v10
	v_and_or_b32 v9, v1, s52, v9
	ds_write_b128 v0, v[2:5]
	ds_write_b128 v0, v[6:9] offset:16
	v_sub_u32_e32 v0, v85, v168
	v_add_u32_e32 v0, v0, v174
	v_sub_u32_e32 v0, v0, v84
	v_lshlrev_b32_e32 v0, 1, v0
	v_and_b32_e32 v0, -4, v0
	v_mad_u32_u24 v166, v84, s67, v0
	s_waitcnt lgkmcnt(0)
	s_barrier
	ds_read2_b32 v[0:1], v166 offset1:1
	ds_read2_b32 v[2:3], v166 offset0:2 offset1:3
	v_lshlrev_b32_e32 v4, 4, v167
	v_add3_u32 v86, v178, v4, s54
	ds_read_b128 v[16:19], v86
	ds_read_b128 v[20:23], v86 offset:32
	ds_read2_b32 v[24:25], v166 offset0:8 offset1:9
	ds_read2_b32 v[26:27], v166 offset0:10 offset1:11
	s_waitcnt lgkmcnt(3)
	v_mfma_f32_32x32x16_bf16 v[0:15], v[0:3], v[16:19], 0
	s_waitcnt lgkmcnt(2)
	v_mov_b32_e32 v136, v20
	v_mov_b32_e32 v137, v21
	v_mov_b32_e32 v138, v22
	v_mov_b32_e32 v139, v23
	v_mov_b32_e32 v140, v16
	v_mov_b32_e32 v141, v17
	v_mov_b32_e32 v142, v18
	s_waitcnt lgkmcnt(0)
	v_mfma_f32_32x32x16_bf16 v[0:15], v[24:27], v[20:23], v[0:15]
	ds_read2_b32 v[32:33], v166 offset0:16 offset1:17
	ds_read2_b32 v[34:35], v166 offset0:18 offset1:19
	ds_read_b128 v[24:27], v86 offset:64
	ds_read_b128 v[28:31], v86 offset:96
	ds_read2_b32 v[36:37], v166 offset0:24 offset1:25
	ds_read2_b32 v[38:39], v166 offset0:26 offset1:27
	v_mov_b32_e32 v143, v19
	s_waitcnt lgkmcnt(3)
	v_mov_b32_e32 v132, v24
	s_waitcnt lgkmcnt(2)
	v_mov_b32_e32 v128, v28
	v_mov_b32_e32 v129, v29
	v_mov_b32_e32 v130, v30
	v_mov_b32_e32 v131, v31
	v_mfma_f32_32x32x16_bf16 v[0:15], v[32:35], v[24:27], v[0:15]
	v_mov_b32_e32 v133, v25
	v_mov_b32_e32 v134, v26
	v_mov_b32_e32 v135, v27
	s_waitcnt lgkmcnt(0)
	v_mfma_f32_32x32x16_bf16 v[0:15], v[36:39], v[28:31], v[0:15]
	ds_read2_b32 v[40:41], v166 offset0:32 offset1:33
	ds_read2_b32 v[42:43], v166 offset0:34 offset1:35
	ds_read_b128 v[32:35], v86 offset:128
	ds_read_b128 v[36:39], v86 offset:160
	ds_read2_b32 v[44:45], v166 offset0:40 offset1:41
	ds_read2_b32 v[46:47], v166 offset0:42 offset1:43
	s_waitcnt lgkmcnt(3)
	v_mov_b32_e32 v124, v32
	s_waitcnt lgkmcnt(2)
	v_mov_b32_e32 v120, v36
	v_mov_b32_e32 v121, v37
	v_mov_b32_e32 v122, v38
	v_mov_b32_e32 v123, v39
	v_mfma_f32_32x32x16_bf16 v[0:15], v[40:43], v[32:35], v[0:15]
	v_mov_b32_e32 v125, v33
	v_mov_b32_e32 v126, v34
	v_mov_b32_e32 v127, v35
	s_waitcnt lgkmcnt(0)
	v_mfma_f32_32x32x16_bf16 v[0:15], v[44:47], v[36:39], v[0:15]
	ds_read2_b32 v[48:49], v166 offset0:48 offset1:49
	ds_read2_b32 v[50:51], v166 offset0:50 offset1:51
	ds_read_b128 v[40:43], v86 offset:192
	ds_read_b128 v[44:47], v86 offset:224
	ds_read2_b32 v[52:53], v166 offset0:56 offset1:57
	ds_read2_b32 v[54:55], v166 offset0:58 offset1:59
	s_waitcnt lgkmcnt(3)
	v_mov_b32_e32 v116, v40
	s_waitcnt lgkmcnt(2)
	v_mov_b32_e32 v112, v44
	v_mov_b32_e32 v113, v45
	v_mov_b32_e32 v114, v46
	v_mov_b32_e32 v115, v47
	v_mfma_f32_32x32x16_bf16 v[0:15], v[48:51], v[40:43], v[0:15]
	v_mov_b32_e32 v117, v41
	v_mov_b32_e32 v118, v42
	v_mov_b32_e32 v119, v43
	s_waitcnt lgkmcnt(0)
	v_mfma_f32_32x32x16_bf16 v[0:15], v[52:55], v[44:47], v[0:15]
	ds_read2_b32 v[56:57], v166 offset0:64 offset1:65
	ds_read2_b32 v[58:59], v166 offset0:66 offset1:67
	ds_read_b128 v[48:51], v86 offset:256
	ds_read_b128 v[52:55], v86 offset:288
	ds_read2_b32 v[60:61], v166 offset0:72 offset1:73
	ds_read2_b32 v[62:63], v166 offset0:74 offset1:75
	s_waitcnt lgkmcnt(3)
	v_mov_b32_e32 v108, v48
	s_waitcnt lgkmcnt(2)
	v_mov_b32_e32 v104, v52
	v_mov_b32_e32 v105, v53
	v_mov_b32_e32 v106, v54
	v_mov_b32_e32 v107, v55
	v_mfma_f32_32x32x16_bf16 v[0:15], v[56:59], v[48:51], v[0:15]
	v_mov_b32_e32 v109, v49
	v_mov_b32_e32 v110, v50
	v_mov_b32_e32 v111, v51
	s_waitcnt lgkmcnt(0)
	v_mfma_f32_32x32x16_bf16 v[0:15], v[60:63], v[52:55], v[0:15]
	ds_read2_b32 v[64:65], v166 offset0:80 offset1:81
	ds_read2_b32 v[66:67], v166 offset0:82 offset1:83
	ds_read_b128 v[56:59], v86 offset:320
	ds_read_b128 v[60:63], v86 offset:352
	ds_read2_b32 v[68:69], v166 offset0:88 offset1:89
	ds_read2_b32 v[70:71], v166 offset0:90 offset1:91
	s_waitcnt lgkmcnt(3)
	v_mov_b32_e32 v100, v56
	s_waitcnt lgkmcnt(2)
	v_mov_b32_e32 v96, v60
	v_mov_b32_e32 v97, v61
	v_mov_b32_e32 v98, v62
	v_mov_b32_e32 v99, v63
	v_mfma_f32_32x32x16_bf16 v[0:15], v[64:67], v[56:59], v[0:15]
	v_mov_b32_e32 v101, v57
	v_mov_b32_e32 v102, v58
	v_mov_b32_e32 v103, v59
	s_waitcnt lgkmcnt(0)
	v_mfma_f32_32x32x16_bf16 v[0:15], v[68:71], v[60:63], v[0:15]
	ds_read2_b32 v[72:73], v166 offset0:96 offset1:97
	ds_read2_b32 v[74:75], v166 offset0:98 offset1:99
	ds_read_b128 v[64:67], v86 offset:384
	ds_read_b128 v[68:71], v86 offset:416
	ds_read2_b32 v[76:77], v166 offset0:104 offset1:105
	ds_read2_b32 v[78:79], v166 offset0:106 offset1:107
	ds_read2_b32 v[80:81], v166 offset0:112 offset1:113
	ds_read2_b32 v[82:83], v166 offset0:114 offset1:115
	s_waitcnt lgkmcnt(5)
	v_mov_b32_e32 v92, v64
	s_waitcnt lgkmcnt(4)
	v_mov_b32_e32 v90, v70
	v_mov_b32_e32 v91, v71
	v_mov_b32_e32 v93, v65
	v_mov_b32_e32 v94, v66
	v_mfma_f32_32x32x16_bf16 v[0:15], v[72:75], v[64:67], v[0:15]
	v_add_u32_e32 v72, v85, v174
	v_mov_b32_e32 v95, v67
	s_waitcnt lgkmcnt(2)
	v_mfma_f32_32x32x16_bf16 v[0:15], v[76:79], v[68:71], v[0:15]
	v_sub_u32_e32 v76, v72, v84
	ds_read_b128 v[72:75], v86 offset:448
	v_sub_u32_e32 v164, v76, v168
	ds_read_b128 v[76:79], v86 offset:480
	ds_read2_b32 v[86:87], v166 offset0:120 offset1:121
	ds_read2_b32 v[88:89], v166 offset0:122 offset1:123
	v_add_u32_e32 v165, 0xffffff00, v164
	s_waitcnt lgkmcnt(3)
	v_mov_b32_e32 v84, v72
	v_mfma_f32_32x32x16_bf16 v[0:15], v[80:83], v[72:75], v[0:15]
	s_waitcnt lgkmcnt(2)
	v_mov_b32_e32 v80, v76
	v_mov_b32_e32 v81, v77
	v_mov_b32_e32 v82, v78
	v_mov_b32_e32 v83, v79
	v_mov_b32_e32 v85, v73
	s_waitcnt lgkmcnt(0)
	v_mfma_f32_32x32x16_bf16 v[0:15], v[86:89], v[76:79], v[0:15]
	v_mov_b32_e32 v86, v74
	v_mov_b32_e32 v87, v75
	v_mov_b32_e32 v88, v68
	v_mov_b32_e32 v89, v69
	v_add_lshl_u32 v224, v165, s4, 1
	v_and_b32_e32 v224, -4, v224
	v_add_u32_e32 v224, v163, v224
	ds_read2_b32 v[192:193], v224 offset1:1
	ds_read2_b32 v[194:195], v224 offset0:2 offset1:3
	ds_read2_b32 v[196:197], v224 offset0:8 offset1:9
	ds_read2_b32 v[198:199], v224 offset0:10 offset1:11
	ds_read2_b32 v[200:201], v224 offset0:16 offset1:17
	ds_read2_b32 v[202:203], v224 offset0:18 offset1:19
	ds_read2_b32 v[204:205], v224 offset0:24 offset1:25
	ds_read2_b32 v[206:207], v224 offset0:26 offset1:27
	ds_read2_b32 v[208:209], v224 offset0:32 offset1:33
	ds_read2_b32 v[210:211], v224 offset0:34 offset1:35
	ds_read2_b32 v[212:213], v224 offset0:40 offset1:41
	ds_read2_b32 v[214:215], v224 offset0:42 offset1:43
